# v44 + non-temporal cache hint on the f32 residual-stream loads and stores of the three residual GEMM epilogues (next read half a layer later; keeps L2 for the bf16 activations)
# baseline (speedup 1.0000x reference)
; __device__ __forceinline__ unsigned cvt_pk_bf16(float lo, float hi) { unsigned r; asm volatile("v_cvt_pk_bf16_f32 %0, %1, %2" : "=v"(r) : "v"(lo), "v"(hi)); return r; }
; __device__ __forceinline__ float shx(float v, int o, int lane) { return __int_as_float(__builtin_amdgcn_ds_bpermute((lane ^ o) << 2, __float_as_int(v))); }
;     __device__ __forceinline__ void operator()(const f32x4 (&acc)[2][2][4][2], const Unit& u, int wr, int wc, int fr, int fq) const {
;         const int bidx = u.pm >> 4, row0 = u.pm * BM + wr * 64 + fr, col0 = u.pn * BM + wc * 32 + 4 * fq, lane = fq * 16 + fr;
;         f32x4 gv[2][2], gs[2][2];
; #pragma unroll
;         for (int bj = 0; bj < 2; ++bj)
; #pragma unroll
;             for (int n = 0; n < 2; ++n) { const int c = col0 + bj * HALF + n * 16; gv[bj][n] = *(const f32x4*)(gate + (size_t)bidx * NMOD + c);
;                 gs[bj][n] = *(const f32x4*)(gnext + c) * (*(const f32x4*)(scn + (size_t)bidx * NMOD + c) + 1.0f); }
; #pragma unroll
;         for (int ai = 0; ai < 2; ++ai)
; #pragma unroll
;             for (int m = 0; m < 4; ++m) { const int row = row0 + ai * HALF + m * 16; const size_t off = (size_t)row * DM + col0; float ss = 0.f;
; #pragma unroll
;                 for (int bj = 0; bj < 2; ++bj)
; #pragma unroll
;                     for (int n = 0; n < 2; ++n) { const f32x4 x = *(const f32x4*)(src + off + bj * HALF + n * 16) + gv[bj][n] * acc[ai][bj][m][n];
;                         *(f32x4*)(dst + off + bj * HALF + n * 16) = x; ss += (x[0] * x[0] + x[1] * x[1]) + (x[2] * x[2] + x[3] * x[3]);
;                         const f32x4 hh = x * gs[bj][n]; u32x2 w; w.x = cvt_pk_bf16(hh[0], hh[1]); w.y = cvt_pk_bf16(hh[2], hh[3]); *(u32x2*)(Hn + off + bj * HALF + n * 16) = w; }
;                 ss += shx(ss, 16, lane); ss += shx(ss, 32, lane);
;                 if (fq == 0) scr[(ai * HALF + wr * 64 + m * 16 + fr) * 4 + wc] = ss; }
.LBB0_536:
	s_ashr_i32 s25, s34, 4
	s_lshl_b32 s34, s34, 8
	s_mul_hi_i32 s27, s25, 0x6000
	s_mulk_i32 s25, 0x6000
	v_lshl_or_b32 v168, s36, 8, v185
	s_add_u32 s36, s57, s25
	s_addc_u32 s37, s58, s27
	s_add_u32 s38, s59, s25
	v_ashrrev_i32_e32 v169, 31, v168
	s_addc_u32 s39, s60, s27
	v_lshlrev_b64 v[76:77], 2, v[168:169]
	v_lshl_add_u64 v[176:177], s[38:39], 0, v[76:77]
	v_lshl_add_u64 v[170:171], s[36:37], 0, v[76:77]
	v_lshl_add_u64 v[174:175], s[20:21], 0, v[76:77]
	global_load_dwordx4 v[76:79], v[176:177], off
	global_load_dwordx4 v[72:75], v[174:175], off
	global_load_dwordx4 v[88:91], v[170:171], off
	s_waitcnt vmcnt(0)
	v_pk_add_f32 v[78:79], v[78:79], 1.0 op_sel_hi:[1,0]
	v_pk_add_f32 v[76:77], v[76:77], 1.0 op_sel_hi:[1,0]
	v_pk_mul_f32 v[164:165], v[74:75], v[78:79]
	v_pk_mul_f32 v[166:167], v[72:73], v[76:77]
	global_load_dwordx4 v[92:95], v[170:171], off offset:64
	global_load_dwordx4 v[72:75], v[174:175], off offset:64
	global_load_dwordx4 v[76:79], v[176:177], off offset:64
	s_waitcnt vmcnt(0)
	v_pk_add_f32 v[78:79], v[78:79], 1.0 op_sel_hi:[1,0]
	v_pk_add_f32 v[76:77], v[76:77], 1.0 op_sel_hi:[1,0]
	v_pk_mul_f32 v[160:161], v[74:75], v[78:79]
	v_pk_mul_f32 v[162:163], v[72:73], v[76:77]
	global_load_dwordx4 v[76:79], v[170:171], off offset:512
	global_load_dwordx4 v[72:75], v[174:175], off offset:512
	global_load_dwordx4 v[152:155], v[176:177], off offset:512
	s_waitcnt vmcnt(0)
	v_pk_add_f32 v[154:155], v[154:155], 1.0 op_sel_hi:[1,0]
	v_pk_add_f32 v[152:153], v[152:153], 1.0 op_sel_hi:[1,0]
	v_pk_mul_f32 v[156:157], v[74:75], v[154:155]
	v_pk_mul_f32 v[158:159], v[72:73], v[152:153]
	global_load_dwordx4 v[72:75], v[170:171], off offset:576
	global_load_dwordx4 v[152:155], v[174:175], off offset:576
	s_nop 0
	global_load_dwordx4 v[174:177], v[176:177], off offset:576
	s_waitcnt vmcnt(0)
	v_pk_add_f32 v[170:171], v[176:177], 1.0 op_sel_hi:[1,0]
	s_nop 0
	v_pk_mul_f32 v[154:155], v[154:155], v[170:171]
	v_add_u32_e32 v170, s34, v180
	v_pk_add_f32 v[174:175], v[174:175], 1.0 op_sel_hi:[1,0]
	v_ashrrev_i32_e32 v171, 31, v170
	v_pk_mul_f32 v[152:153], v[152:153], v[174:175]
	v_lshlrev_b64 v[174:175], 10, v[170:171]
	v_lshl_add_u64 v[192:193], v[174:175], 0, v[168:169]
	v_lshlrev_b64 v[194:195], 2, v[192:193]
	v_lshl_add_u64 v[178:179], s[4:5], 0, v[194:195]
	v_mov_b32_e32 v228, v194
	v_mov_b32_e32 v229, v228
	global_load_dwordx4 v[196:199], v229, s[4:5] nt
	global_load_dwordx4 v[200:203], v229, s[4:5] offset:64 nt
	global_load_dwordx4 v[204:207], v229, s[4:5] offset:512 nt
	global_load_dwordx4 v[208:211], v229, s[4:5] offset:576 nt
	v_add_u32_e32 v229, 0x10000, v228
	global_load_dwordx4 v[212:215], v229, s[4:5] nt
	global_load_dwordx4 v[216:219], v229, s[4:5] offset:64 nt
	global_load_dwordx4 v[220:223], v229, s[4:5] offset:512 nt
	global_load_dwordx4 v[224:227], v229, s[4:5] offset:576 nt
	s_waitcnt vmcnt(7)
	v_pk_fma_f32 v[176:177], v[142:143], v[90:91], v[198:199]
	v_pk_fma_f32 v[174:175], v[140:141], v[88:89], v[196:197]
	v_mul_f32_e32 v143, v177, v177
	v_mul_f32_e32 v142, v175, v175
	v_lshl_add_u64 v[140:141], s[12:13], 0, v[194:195]
	v_fmac_f32_e32 v142, v174, v174
	v_fmac_f32_e32 v143, v176, v176
	global_store_dwordx4 v[140:141], v[174:177], off nt
	v_add_f32_e32 v194, v142, v143
	v_pk_mul_f32 v[142:143], v[164:165], v[176:177]
	v_pk_mul_f32 v[174:175], v[166:167], v[174:175]
	s_nop 0
	v_cvt_pk_bf16_f32 v174, v174, v175
	v_cvt_pk_bf16_f32 v175, v142, v143
	v_lshl_add_u64 v[142:143], v[192:193], 1, s[18:19]
	global_store_dwordx2 v[142:143], v[174:175], off
	s_waitcnt vmcnt(8)
	v_pk_fma_f32 v[136:137], v[136:137], v[92:93], v[200:201]
	v_pk_fma_f32 v[138:139], v[138:139], v[94:95], v[202:203]
	v_mul_f32_e32 v174, v137, v137
	global_store_dwordx4 v[140:141], v[136:139], off offset:64 nt
	v_fmac_f32_e32 v174, v136, v136
	v_mul_f32_e32 v175, v139, v139
	v_pk_mul_f32 v[136:137], v[162:163], v[136:137]
	v_fmac_f32_e32 v175, v138, v138
	v_pk_mul_f32 v[138:139], v[160:161], v[138:139]
	v_cvt_pk_bf16_f32 v136, v136, v137
	v_add_f32_e32 v174, v174, v175
	v_cvt_pk_bf16_f32 v137, v138, v139
	global_store_dwordx2 v[142:143], v[136:137], off offset:32
	v_add_f32_e32 v174, v194, v174
	s_waitcnt vmcnt(9)
	v_pk_fma_f32 v[132:133], v[132:133], v[76:77], v[204:205]
	v_pk_fma_f32 v[134:135], v[134:135], v[78:79], v[206:207]
	v_mul_f32_e32 v136, v133, v133
	global_store_dwordx4 v[140:141], v[132:135], off offset:512 nt
	v_fmac_f32_e32 v136, v132, v132
	v_mul_f32_e32 v137, v135, v135
	v_pk_mul_f32 v[132:133], v[158:159], v[132:133]
	v_fmac_f32_e32 v137, v134, v134
	v_pk_mul_f32 v[134:135], v[156:157], v[134:135]
	v_cvt_pk_bf16_f32 v132, v132, v133
	v_add_f32_e32 v136, v136, v137
	v_cvt_pk_bf16_f32 v133, v134, v135
	global_store_dwordx2 v[142:143], v[132:133], off offset:256
	v_add_f32_e32 v136, v174, v136
	s_waitcnt vmcnt(10)
	v_pk_fma_f32 v[130:131], v[130:131], v[74:75], v[210:211]
	v_pk_fma_f32 v[128:129], v[128:129], v[72:73], v[208:209]
	v_add_u32_e32 v229, 0x20000, v228
	global_load_dwordx4 v[196:199], v229, s[4:5] nt
	global_load_dwordx4 v[200:203], v229, s[4:5] offset:64 nt
	global_load_dwordx4 v[204:207], v229, s[4:5] offset:512 nt
	global_load_dwordx4 v[208:211], v229, s[4:5] offset:576 nt
	v_mul_f32_e32 v133, v131, v131
	v_mul_f32_e32 v132, v129, v129
	v_fmac_f32_e32 v132, v128, v128
	v_fmac_f32_e32 v133, v130, v130
	global_store_dwordx4 v[140:141], v[128:131], off offset:576 nt
	v_add_f32_e32 v132, v132, v133
	v_add_f32_e32 v132, v136, v132
	v_pk_mul_f32 v[128:129], v[152:153], v[128:129]
	v_pk_mul_f32 v[130:131], v[154:155], v[130:131]
	v_cvt_pk_bf16_f32 v128, v128, v129
	s_nop 0
	v_cvt_pk_bf16_f32 v129, v130, v131
	global_store_dwordx2 v[142:143], v[128:129], off offset:288
	ds_bpermute_b32 v128, v182, v132
	s_waitcnt lgkmcnt(0)
	v_add_f32_e32 v128, v132, v128
	ds_bpermute_b32 v129, v183, v128
	s_and_saveexec_b64 s[36:37], s[6:7]
	s_cbranch_execz .LBB0_538
	s_waitcnt lgkmcnt(0)
	v_add_f32_e32 v128, v128, v129
	ds_write_b32 v184, v128
; __device__ __forceinline__ unsigned cvt_pk_bf16(float lo, float hi) { unsigned r; asm volatile("v_cvt_pk_bf16_f32 %0, %1, %2" : "=v"(r) : "v"(lo), "v"(hi)); return r; }
; __device__ __forceinline__ float shx(float v, int o, int lane) { return __int_as_float(__builtin_amdgcn_ds_bpermute((lane ^ o) << 2, __float_as_int(v))); }
;     __device__ __forceinline__ void operator()(const f32x4 (&acc)[2][2][4][2], const Unit& u, int wr, int wc, int fr, int fq) const {
;     ...
;             for (int m = 0; m < 4; ++m) { const int row = row0 + ai * HALF + m * 16; const size_t off = (size_t)row * DM + col0; float ss = 0.f;
; #pragma unroll
;                 for (int bj = 0; bj < 2; ++bj)
; #pragma unroll
;                     for (int n = 0; n < 2; ++n) { const f32x4 x = *(const f32x4*)(src + off + bj * HALF + n * 16) + gv[bj][n] * acc[ai][bj][m][n];
;                         *(f32x4*)(dst + off + bj * HALF + n * 16) = x; ss += (x[0] * x[0] + x[1] * x[1]) + (x[2] * x[2] + x[3] * x[3]);
;                         const f32x4 hh = x * gs[bj][n]; u32x2 w; w.x = cvt_pk_bf16(hh[0], hh[1]); w.y = cvt_pk_bf16(hh[2], hh[3]); *(u32x2*)(Hn + off + bj * HALF + n * 16) = w; }
;                 ss += shx(ss, 16, lane); ss += shx(ss, 32, lane);
;                 if (fq == 0) scr[(ai * HALF + wr * 64 + m * 16 + fr) * 4 + wc] = ss; }
.LBB0_538:
	s_or_b64 exec, exec, s[36:37]
	v_or_b32_e32 v128, 16, v170
	s_waitcnt lgkmcnt(0)
	v_ashrrev_i32_e32 v129, 31, v128
	v_lshlrev_b64 v[128:129], 10, v[128:129]
	v_lshl_add_u64 v[132:133], v[128:129], 0, v[168:169]
	v_lshlrev_b64 v[134:135], 2, v[132:133]
	v_lshl_add_u64 v[136:137], s[4:5], 0, v[134:135]
	v_lshl_add_u64 v[132:133], v[132:133], 1, s[18:19]
	v_lshl_add_u64 v[134:135], s[12:13], 0, v[134:135]
	s_waitcnt vmcnt(15)
	v_pk_fma_f32 v[124:125], v[124:125], v[88:89], v[212:213]
	v_pk_fma_f32 v[126:127], v[126:127], v[90:91], v[214:215]
	v_pk_mul_f32 v[130:131], v[166:167], v[124:125]
	global_store_dwordx4 v[134:135], v[124:127], off nt
	v_pk_mul_f32 v[128:129], v[164:165], v[126:127]
	v_cvt_pk_bf16_f32 v130, v130, v131
	s_nop 0
	v_cvt_pk_bf16_f32 v131, v128, v129
	global_store_dwordx2 v[132:133], v[130:131], off
	v_mul_f32_e32 v125, v125, v125
	v_mul_f32_e32 v127, v127, v127
	v_fmac_f32_e32 v125, v124, v124
	v_fmac_f32_e32 v127, v126, v126
	v_add_f32_e32 v124, v125, v127
	s_waitcnt vmcnt(16)
	v_pk_fma_f32 v[120:121], v[120:121], v[92:93], v[216:217]
	v_pk_fma_f32 v[122:123], v[122:123], v[94:95], v[218:219]
	v_pk_mul_f32 v[130:131], v[162:163], v[120:121]
	global_store_dwordx4 v[134:135], v[120:123], off offset:64 nt
	v_pk_mul_f32 v[128:129], v[160:161], v[122:123]
	v_cvt_pk_bf16_f32 v130, v130, v131
	s_nop 0
	v_cvt_pk_bf16_f32 v131, v128, v129
	global_store_dwordx2 v[132:133], v[130:131], off offset:32
	v_mul_f32_e32 v121, v121, v121
	v_mul_f32_e32 v123, v123, v123
	v_fmac_f32_e32 v121, v120, v120
	v_fmac_f32_e32 v123, v122, v122
	v_add_f32_e32 v120, v121, v123
	v_add_f32_e32 v120, v124, v120
	s_waitcnt vmcnt(17)
	v_pk_fma_f32 v[116:117], v[116:117], v[76:77], v[220:221]
	v_pk_fma_f32 v[118:119], v[118:119], v[78:79], v[222:223]
	v_pk_mul_f32 v[130:131], v[158:159], v[116:117]
	global_store_dwordx4 v[134:135], v[116:119], off offset:512 nt
	v_pk_mul_f32 v[128:129], v[156:157], v[118:119]
	v_cvt_pk_bf16_f32 v130, v130, v131
	s_nop 0
	v_cvt_pk_bf16_f32 v131, v128, v129
	global_store_dwordx2 v[132:133], v[130:131], off offset:256
	v_mul_f32_e32 v117, v117, v117
	v_mul_f32_e32 v119, v119, v119
	v_fmac_f32_e32 v117, v116, v116
	v_fmac_f32_e32 v119, v118, v118
	v_add_f32_e32 v116, v117, v119
	v_add_f32_e32 v118, v120, v116
	s_waitcnt vmcnt(18)
	v_pk_fma_f32 v[116:117], v[114:115], v[74:75], v[226:227]
	v_pk_fma_f32 v[114:115], v[112:113], v[72:73], v[224:225]
	v_add_u32_e32 v229, 0x30000, v228
	global_load_dwordx4 v[212:215], v229, s[4:5] nt
	global_load_dwordx4 v[216:219], v229, s[4:5] offset:64 nt
	global_load_dwordx4 v[220:223], v229, s[4:5] offset:512 nt
	global_load_dwordx4 v[224:227], v229, s[4:5] offset:576 nt
	v_mul_f32_e32 v113, v117, v117
	v_mul_f32_e32 v112, v115, v115
	v_fmac_f32_e32 v112, v114, v114
	v_fmac_f32_e32 v113, v116, v116
	v_add_f32_e32 v112, v112, v113
	v_add_f32_e32 v112, v118, v112
	ds_bpermute_b32 v113, v182, v112
	global_store_dwordx4 v[134:135], v[114:117], off offset:576 nt
	s_waitcnt lgkmcnt(0)
	v_add_f32_e32 v112, v112, v113
	ds_bpermute_b32 v113, v183, v112
	v_pk_mul_f32 v[114:115], v[152:153], v[114:115]
	v_pk_mul_f32 v[116:117], v[154:155], v[116:117]
	v_cvt_pk_bf16_f32 v114, v114, v115
	s_nop 0
	v_cvt_pk_bf16_f32 v115, v116, v117
	global_store_dwordx2 v[132:133], v[114:115], off offset:288
	s_and_saveexec_b64 s[36:37], s[6:7]
	s_cbranch_execz .LBB0_540
	s_waitcnt lgkmcnt(0)
	v_add_f32_e32 v112, v112, v113
	ds_write_b32 v184, v112 offset:256
.LBB0_540:
	s_or_b64 exec, exec, s[36:37]
	v_or_b32_e32 v112, 32, v170
	s_waitcnt lgkmcnt(0)
	v_ashrrev_i32_e32 v113, 31, v112
	v_lshlrev_b64 v[112:113], 10, v[112:113]
	v_lshl_add_u64 v[116:117], v[112:113], 0, v[168:169]
	v_lshlrev_b64 v[118:119], 2, v[116:117]
	v_lshl_add_u64 v[120:121], s[4:5], 0, v[118:119]
	v_lshl_add_u64 v[116:117], v[116:117], 1, s[18:19]
	v_lshl_add_u64 v[118:119], s[12:13], 0, v[118:119]
	s_waitcnt vmcnt(17)
	v_pk_fma_f32 v[108:109], v[108:109], v[88:89], v[196:197]
	v_pk_fma_f32 v[110:111], v[110:111], v[90:91], v[198:199]
	v_pk_mul_f32 v[114:115], v[166:167], v[108:109]
	global_store_dwordx4 v[118:119], v[108:111], off nt
	v_pk_mul_f32 v[112:113], v[164:165], v[110:111]
	v_cvt_pk_bf16_f32 v114, v114, v115
	s_nop 0
	v_cvt_pk_bf16_f32 v115, v112, v113
	global_store_dwordx2 v[116:117], v[114:115], off
	v_mul_f32_e32 v109, v109, v109
	v_mul_f32_e32 v111, v111, v111
	v_fmac_f32_e32 v109, v108, v108
	v_fmac_f32_e32 v111, v110, v110
	v_add_f32_e32 v108, v109, v111
	s_waitcnt vmcnt(18)
	v_pk_fma_f32 v[104:105], v[104:105], v[92:93], v[200:201]
	v_pk_fma_f32 v[106:107], v[106:107], v[94:95], v[202:203]
	v_pk_mul_f32 v[114:115], v[162:163], v[104:105]
	global_store_dwordx4 v[118:119], v[104:107], off offset:64 nt
	v_pk_mul_f32 v[112:113], v[160:161], v[106:107]
	v_cvt_pk_bf16_f32 v114, v114, v115
	s_nop 0
	v_cvt_pk_bf16_f32 v115, v112, v113
	global_store_dwordx2 v[116:117], v[114:115], off offset:32
	v_mul_f32_e32 v105, v105, v105
	v_mul_f32_e32 v107, v107, v107
	v_fmac_f32_e32 v105, v104, v104
	v_fmac_f32_e32 v107, v106, v106
	v_add_f32_e32 v104, v105, v107
	v_add_f32_e32 v104, v108, v104
	s_waitcnt vmcnt(19)
	v_pk_fma_f32 v[100:101], v[100:101], v[76:77], v[204:205]
	v_pk_fma_f32 v[102:103], v[102:103], v[78:79], v[206:207]
	v_pk_mul_f32 v[114:115], v[158:159], v[100:101]
	global_store_dwordx4 v[118:119], v[100:103], off offset:512 nt
	v_pk_mul_f32 v[112:113], v[156:157], v[102:103]
	v_cvt_pk_bf16_f32 v114, v114, v115
	s_nop 0
	v_cvt_pk_bf16_f32 v115, v112, v113
	global_store_dwordx2 v[116:117], v[114:115], off offset:256
	v_mul_f32_e32 v101, v101, v101
	v_mul_f32_e32 v103, v103, v103
	v_fmac_f32_e32 v101, v100, v100
	v_fmac_f32_e32 v103, v102, v102
	v_add_f32_e32 v100, v101, v103
	v_add_f32_e32 v102, v104, v100
	s_waitcnt vmcnt(20)
	v_pk_fma_f32 v[100:101], v[98:99], v[74:75], v[210:211]
	v_pk_fma_f32 v[98:99], v[96:97], v[72:73], v[208:209]
	v_add_u32_e32 v229, 0x80000, v228
	global_load_dwordx4 v[196:199], v229, s[4:5] nt
	global_load_dwordx4 v[200:203], v229, s[4:5] offset:64 nt
	global_load_dwordx4 v[204:207], v229, s[4:5] offset:512 nt
	global_load_dwordx4 v[208:211], v229, s[4:5] offset:576 nt
	v_mul_f32_e32 v97, v101, v101
	v_mul_f32_e32 v96, v99, v99
	v_fmac_f32_e32 v96, v98, v98
	v_fmac_f32_e32 v97, v100, v100
	v_add_f32_e32 v96, v96, v97
	v_add_f32_e32 v96, v102, v96
	ds_bpermute_b32 v97, v182, v96
	global_store_dwordx4 v[118:119], v[98:101], off offset:576 nt
	s_waitcnt lgkmcnt(0)
	v_add_f32_e32 v96, v96, v97
	ds_bpermute_b32 v97, v183, v96
	v_pk_mul_f32 v[98:99], v[152:153], v[98:99]
	v_pk_mul_f32 v[100:101], v[154:155], v[100:101]
	v_cvt_pk_bf16_f32 v98, v98, v99
	s_nop 0
	v_cvt_pk_bf16_f32 v99, v100, v101
	global_store_dwordx2 v[116:117], v[98:99], off offset:288
	s_and_saveexec_b64 s[36:37], s[6:7]
	s_mov_b32 s70, 0xbf3a00e3
	s_cbranch_execz .LBB0_542
	s_waitcnt lgkmcnt(0)
	v_add_f32_e32 v96, v96, v97
	ds_write_b32 v184, v96 offset:512
; __device__ __forceinline__ unsigned cvt_pk_bf16(float lo, float hi) { unsigned r; asm volatile("v_cvt_pk_bf16_f32 %0, %1, %2" : "=v"(r) : "v"(lo), "v"(hi)); return r; }
; __device__ __forceinline__ float shx(float v, int o, int lane) { return __int_as_float(__builtin_amdgcn_ds_bpermute((lane ^ o) << 2, __float_as_int(v))); }
;     __device__ __forceinline__ void operator()(const f32x4 (&acc)[2][2][4][2], const Unit& u, int wr, int wc, int fr, int fq) const {
;     ...
;             for (int m = 0; m < 4; ++m) { const int row = row0 + ai * HALF + m * 16; const size_t off = (size_t)row * DM + col0; float ss = 0.f;
; #pragma unroll
;                 for (int bj = 0; bj < 2; ++bj)
; #pragma unroll
;                     for (int n = 0; n < 2; ++n) { const f32x4 x = *(const f32x4*)(src + off + bj * HALF + n * 16) + gv[bj][n] * acc[ai][bj][m][n];
;                         *(f32x4*)(dst + off + bj * HALF + n * 16) = x; ss += (x[0] * x[0] + x[1] * x[1]) + (x[2] * x[2] + x[3] * x[3]);
;                         const f32x4 hh = x * gs[bj][n]; u32x2 w; w.x = cvt_pk_bf16(hh[0], hh[1]); w.y = cvt_pk_bf16(hh[2], hh[3]); *(u32x2*)(Hn + off + bj * HALF + n * 16) = w; }
;                 ss += shx(ss, 16, lane); ss += shx(ss, 32, lane);
;                 if (fq == 0) scr[(ai * HALF + wr * 64 + m * 16 + fr) * 4 + wc] = ss; }
.LBB0_542:
	s_or_b64 exec, exec, s[36:37]
	v_or_b32_e32 v96, 48, v170
	s_waitcnt lgkmcnt(0)
	v_ashrrev_i32_e32 v97, 31, v96
	v_lshlrev_b64 v[96:97], 10, v[96:97]
	v_lshl_add_u64 v[100:101], v[96:97], 0, v[168:169]
	v_lshlrev_b64 v[102:103], 2, v[100:101]
	v_lshl_add_u64 v[104:105], s[4:5], 0, v[102:103]
	v_lshl_add_u64 v[100:101], v[100:101], 1, s[18:19]
	v_lshl_add_u64 v[102:103], s[12:13], 0, v[102:103]
	s_waitcnt vmcnt(17)
	v_pk_fma_f32 v[84:85], v[84:85], v[88:89], v[212:213]
	v_pk_fma_f32 v[86:87], v[86:87], v[90:91], v[214:215]
	v_pk_mul_f32 v[98:99], v[166:167], v[84:85]
	global_store_dwordx4 v[102:103], v[84:87], off nt
	v_pk_mul_f32 v[96:97], v[164:165], v[86:87]
	v_cvt_pk_bf16_f32 v98, v98, v99
	s_nop 0
	v_cvt_pk_bf16_f32 v99, v96, v97
	global_store_dwordx2 v[100:101], v[98:99], off
	v_mul_f32_e32 v85, v85, v85
	v_mul_f32_e32 v87, v87, v87
	v_fmac_f32_e32 v85, v84, v84
	v_fmac_f32_e32 v87, v86, v86
	v_add_f32_e32 v84, v85, v87
	s_waitcnt vmcnt(18)
	v_pk_fma_f32 v[80:81], v[80:81], v[92:93], v[216:217]
	v_pk_fma_f32 v[82:83], v[82:83], v[94:95], v[218:219]
	v_pk_mul_f32 v[98:99], v[162:163], v[80:81]
	global_store_dwordx4 v[102:103], v[80:83], off offset:64 nt
	v_pk_mul_f32 v[96:97], v[160:161], v[82:83]
	v_cvt_pk_bf16_f32 v98, v98, v99
	s_nop 0
	v_cvt_pk_bf16_f32 v99, v96, v97
	global_store_dwordx2 v[100:101], v[98:99], off offset:32
	v_mul_f32_e32 v81, v81, v81
	v_mul_f32_e32 v83, v83, v83
	v_fmac_f32_e32 v81, v80, v80
	v_fmac_f32_e32 v83, v82, v82
	v_add_f32_e32 v80, v81, v83
	v_add_f32_e32 v80, v84, v80
	s_waitcnt vmcnt(19)
	v_pk_fma_f32 v[68:69], v[68:69], v[76:77], v[220:221]
	v_pk_fma_f32 v[70:71], v[70:71], v[78:79], v[222:223]
	v_pk_mul_f32 v[98:99], v[158:159], v[68:69]
	global_store_dwordx4 v[102:103], v[68:71], off offset:512 nt
	v_pk_mul_f32 v[96:97], v[156:157], v[70:71]
	v_cvt_pk_bf16_f32 v98, v98, v99
	s_nop 0
	v_cvt_pk_bf16_f32 v99, v96, v97
	global_store_dwordx2 v[100:101], v[98:99], off offset:256
	v_mul_f32_e32 v69, v69, v69
	v_mul_f32_e32 v71, v71, v71
	v_fmac_f32_e32 v69, v68, v68
	v_fmac_f32_e32 v71, v70, v70
	v_add_f32_e32 v68, v69, v71
	v_add_f32_e32 v70, v80, v68
	s_waitcnt vmcnt(20)
	v_pk_fma_f32 v[68:69], v[66:67], v[74:75], v[226:227]
	v_pk_fma_f32 v[66:67], v[64:65], v[72:73], v[224:225]
	v_add_u32_e32 v229, 0x90000, v228
	global_load_dwordx4 v[212:215], v229, s[4:5] nt
	global_load_dwordx4 v[216:219], v229, s[4:5] offset:64 nt
	global_load_dwordx4 v[220:223], v229, s[4:5] offset:512 nt
	global_load_dwordx4 v[224:227], v229, s[4:5] offset:576 nt
	v_mul_f32_e32 v65, v69, v69
	v_mul_f32_e32 v64, v67, v67
	v_fmac_f32_e32 v64, v66, v66
	v_fmac_f32_e32 v65, v68, v68
	v_add_f32_e32 v64, v64, v65
	v_add_f32_e32 v64, v70, v64
	ds_bpermute_b32 v65, v182, v64
	global_store_dwordx4 v[102:103], v[66:69], off offset:576 nt
	s_waitcnt lgkmcnt(0)
	v_add_f32_e32 v64, v64, v65
	ds_bpermute_b32 v65, v183, v64
	v_pk_mul_f32 v[66:67], v[152:153], v[66:67]
	v_pk_mul_f32 v[68:69], v[154:155], v[68:69]
	v_cvt_pk_bf16_f32 v66, v66, v67
	s_nop 0
	v_cvt_pk_bf16_f32 v67, v68, v69
	global_store_dwordx2 v[100:101], v[66:67], off offset:288
	s_and_saveexec_b64 s[36:37], s[6:7]
	s_cbranch_execz .LBB0_544
	s_waitcnt lgkmcnt(0)
	v_add_f32_e32 v64, v64, v65
	ds_write_b32 v184, v64 offset:768
.LBB0_544:
	s_or_b64 exec, exec, s[36:37]
	s_waitcnt lgkmcnt(0)
	v_lshlrev_b64 v[64:65], 10, v[170:171]
	v_lshl_add_u64 v[64:65], v[64:65], 0, v[168:169]
	s_mov_b64 s[36:37], 0x20000
	v_lshl_add_u64 v[70:71], v[64:65], 0, s[36:37]
	v_lshlrev_b64 v[80:81], 2, v[70:71]
	v_lshl_add_u64 v[82:83], s[4:5], 0, v[80:81]
	v_lshl_add_u64 v[70:71], v[70:71], 1, s[18:19]
	v_lshl_add_u64 v[80:81], s[12:13], 0, v[80:81]
	s_waitcnt vmcnt(17)
	v_pk_fma_f32 v[60:61], v[60:61], v[88:89], v[196:197]
	v_pk_fma_f32 v[62:63], v[62:63], v[90:91], v[198:199]
	v_pk_mul_f32 v[68:69], v[166:167], v[60:61]
	global_store_dwordx4 v[80:81], v[60:63], off nt
	v_pk_mul_f32 v[66:67], v[164:165], v[62:63]
	v_cvt_pk_bf16_f32 v68, v68, v69
	s_nop 0
	v_cvt_pk_bf16_f32 v69, v66, v67
	global_store_dwordx2 v[70:71], v[68:69], off
	v_mul_f32_e32 v61, v61, v61
	v_mul_f32_e32 v63, v63, v63
	v_fmac_f32_e32 v61, v60, v60
	v_fmac_f32_e32 v63, v62, v62
	v_add_f32_e32 v60, v61, v63
	s_waitcnt vmcnt(18)
	v_pk_fma_f32 v[56:57], v[56:57], v[92:93], v[200:201]
	v_pk_fma_f32 v[58:59], v[58:59], v[94:95], v[202:203]
	v_pk_mul_f32 v[68:69], v[162:163], v[56:57]
	global_store_dwordx4 v[80:81], v[56:59], off offset:64 nt
	v_pk_mul_f32 v[66:67], v[160:161], v[58:59]
	v_cvt_pk_bf16_f32 v68, v68, v69
	s_nop 0
	v_cvt_pk_bf16_f32 v69, v66, v67
	global_store_dwordx2 v[70:71], v[68:69], off offset:32
	v_mul_f32_e32 v57, v57, v57
	v_mul_f32_e32 v59, v59, v59
	v_fmac_f32_e32 v57, v56, v56
	v_fmac_f32_e32 v59, v58, v58
	v_add_f32_e32 v56, v57, v59
	v_add_f32_e32 v56, v60, v56
	s_waitcnt vmcnt(19)
	v_pk_fma_f32 v[52:53], v[52:53], v[76:77], v[204:205]
	v_pk_fma_f32 v[54:55], v[54:55], v[78:79], v[206:207]
	v_pk_mul_f32 v[68:69], v[158:159], v[52:53]
	global_store_dwordx4 v[80:81], v[52:55], off offset:512 nt
	v_pk_mul_f32 v[66:67], v[156:157], v[54:55]
	v_cvt_pk_bf16_f32 v68, v68, v69
	s_nop 0
	v_cvt_pk_bf16_f32 v69, v66, v67
	global_store_dwordx2 v[70:71], v[68:69], off offset:256
	v_mul_f32_e32 v53, v53, v53
	v_mul_f32_e32 v55, v55, v55
	v_fmac_f32_e32 v53, v52, v52
	v_fmac_f32_e32 v55, v54, v54
	v_add_f32_e32 v52, v53, v55
	v_add_f32_e32 v54, v56, v52
	s_waitcnt vmcnt(20)
	v_pk_fma_f32 v[52:53], v[50:51], v[74:75], v[210:211]
	v_pk_fma_f32 v[50:51], v[48:49], v[72:73], v[208:209]
	v_add_u32_e32 v229, 0xa0000, v228
	global_load_dwordx4 v[196:199], v229, s[4:5] nt
	global_load_dwordx4 v[200:203], v229, s[4:5] offset:64 nt
	global_load_dwordx4 v[204:207], v229, s[4:5] offset:512 nt
	global_load_dwordx4 v[208:211], v229, s[4:5] offset:576 nt
	v_mul_f32_e32 v49, v53, v53
	v_mul_f32_e32 v48, v51, v51
	v_fmac_f32_e32 v48, v50, v50
	v_fmac_f32_e32 v49, v52, v52
	v_add_f32_e32 v48, v48, v49
	v_add_f32_e32 v48, v54, v48
	ds_bpermute_b32 v49, v182, v48
	global_store_dwordx4 v[80:81], v[50:53], off offset:576 nt
	s_waitcnt lgkmcnt(0)
	v_add_f32_e32 v48, v48, v49
	ds_bpermute_b32 v49, v183, v48
	v_pk_mul_f32 v[50:51], v[152:153], v[50:51]
	v_pk_mul_f32 v[52:53], v[154:155], v[52:53]
	v_cvt_pk_bf16_f32 v50, v50, v51
	s_nop 0
	v_cvt_pk_bf16_f32 v51, v52, v53
	global_store_dwordx2 v[70:71], v[50:51], off offset:288
	s_and_saveexec_b64 s[36:37], s[6:7]
	s_cbranch_execz .LBB0_546
	s_waitcnt lgkmcnt(0)
	v_add_f32_e32 v48, v48, v49
	ds_write_b32 v184, v48 offset:2048
; __device__ __forceinline__ unsigned cvt_pk_bf16(float lo, float hi) { unsigned r; asm volatile("v_cvt_pk_bf16_f32 %0, %1, %2" : "=v"(r) : "v"(lo), "v"(hi)); return r; }
; __device__ __forceinline__ float shx(float v, int o, int lane) { return __int_as_float(__builtin_amdgcn_ds_bpermute((lane ^ o) << 2, __float_as_int(v))); }
;     __device__ __forceinline__ void operator()(const f32x4 (&acc)[2][2][4][2], const Unit& u, int wr, int wc, int fr, int fq) const {
;     ...
;             for (int m = 0; m < 4; ++m) { const int row = row0 + ai * HALF + m * 16; const size_t off = (size_t)row * DM + col0; float ss = 0.f;
; #pragma unroll
;                 for (int bj = 0; bj < 2; ++bj)
; #pragma unroll
;                     for (int n = 0; n < 2; ++n) { const f32x4 x = *(const f32x4*)(src + off + bj * HALF + n * 16) + gv[bj][n] * acc[ai][bj][m][n];
;                         *(f32x4*)(dst + off + bj * HALF + n * 16) = x; ss += (x[0] * x[0] + x[1] * x[1]) + (x[2] * x[2] + x[3] * x[3]);
;                         const f32x4 hh = x * gs[bj][n]; u32x2 w; w.x = cvt_pk_bf16(hh[0], hh[1]); w.y = cvt_pk_bf16(hh[2], hh[3]); *(u32x2*)(Hn + off + bj * HALF + n * 16) = w; }
;                 ss += shx(ss, 16, lane); ss += shx(ss, 32, lane);
;                 if (fq == 0) scr[(ai * HALF + wr * 64 + m * 16 + fr) * 4 + wc] = ss; }
.LBB0_546:
	s_or_b64 exec, exec, s[36:37]
	s_mov_b64 s[36:37], 0x24000
	v_lshl_add_u64 v[52:53], v[64:65], 0, s[36:37]
	v_lshlrev_b64 v[54:55], 2, v[52:53]
	v_lshl_add_u64 v[56:57], s[4:5], 0, v[54:55]
	s_waitcnt lgkmcnt(0)
	v_lshl_add_u64 v[52:53], v[52:53], 1, s[18:19]
	v_lshl_add_u64 v[54:55], s[12:13], 0, v[54:55]
	s_waitcnt vmcnt(17)
	v_pk_fma_f32 v[44:45], v[44:45], v[88:89], v[212:213]
	v_pk_fma_f32 v[46:47], v[46:47], v[90:91], v[214:215]
	v_pk_mul_f32 v[50:51], v[166:167], v[44:45]
	global_store_dwordx4 v[54:55], v[44:47], off nt
	v_pk_mul_f32 v[48:49], v[164:165], v[46:47]
	v_cvt_pk_bf16_f32 v50, v50, v51
	s_nop 0
	v_cvt_pk_bf16_f32 v51, v48, v49
	global_store_dwordx2 v[52:53], v[50:51], off
	v_mul_f32_e32 v45, v45, v45
	v_mul_f32_e32 v47, v47, v47
	v_fmac_f32_e32 v45, v44, v44
	v_fmac_f32_e32 v47, v46, v46
	v_add_f32_e32 v44, v45, v47
	s_waitcnt vmcnt(18)
	v_pk_fma_f32 v[40:41], v[40:41], v[92:93], v[216:217]
	v_pk_fma_f32 v[42:43], v[42:43], v[94:95], v[218:219]
	v_pk_mul_f32 v[50:51], v[162:163], v[40:41]
	global_store_dwordx4 v[54:55], v[40:43], off offset:64 nt
	v_pk_mul_f32 v[48:49], v[160:161], v[42:43]
	v_cvt_pk_bf16_f32 v50, v50, v51
	s_nop 0
	v_cvt_pk_bf16_f32 v51, v48, v49
	global_store_dwordx2 v[52:53], v[50:51], off offset:32
	v_mul_f32_e32 v41, v41, v41
	v_mul_f32_e32 v43, v43, v43
	v_fmac_f32_e32 v41, v40, v40
	v_fmac_f32_e32 v43, v42, v42
	v_add_f32_e32 v40, v41, v43
	v_add_f32_e32 v40, v44, v40
	s_waitcnt vmcnt(19)
	v_pk_fma_f32 v[36:37], v[36:37], v[76:77], v[220:221]
	v_pk_fma_f32 v[38:39], v[38:39], v[78:79], v[222:223]
	v_pk_mul_f32 v[50:51], v[158:159], v[36:37]
	global_store_dwordx4 v[54:55], v[36:39], off offset:512 nt
	v_pk_mul_f32 v[48:49], v[156:157], v[38:39]
	v_cvt_pk_bf16_f32 v50, v50, v51
	s_nop 0
	v_cvt_pk_bf16_f32 v51, v48, v49
	global_store_dwordx2 v[52:53], v[50:51], off offset:256
	v_mul_f32_e32 v37, v37, v37
	v_mul_f32_e32 v39, v39, v39
	v_fmac_f32_e32 v37, v36, v36
	v_fmac_f32_e32 v39, v38, v38
	v_add_f32_e32 v36, v37, v39
	v_add_f32_e32 v38, v40, v36
	s_waitcnt vmcnt(20)
	v_pk_fma_f32 v[36:37], v[34:35], v[74:75], v[226:227]
	v_pk_fma_f32 v[34:35], v[32:33], v[72:73], v[224:225]
	v_add_u32_e32 v229, 0xb0000, v228
	global_load_dwordx4 v[212:215], v229, s[4:5] nt
	global_load_dwordx4 v[216:219], v229, s[4:5] offset:64 nt
	global_load_dwordx4 v[220:223], v229, s[4:5] offset:512 nt
	global_load_dwordx4 v[224:227], v229, s[4:5] offset:576 nt
	v_mul_f32_e32 v33, v37, v37
	v_mul_f32_e32 v32, v35, v35
	v_fmac_f32_e32 v32, v34, v34
	v_fmac_f32_e32 v33, v36, v36
	v_add_f32_e32 v32, v32, v33
	v_add_f32_e32 v32, v38, v32
	ds_bpermute_b32 v33, v182, v32
	global_store_dwordx4 v[54:55], v[34:37], off offset:576 nt
	s_waitcnt lgkmcnt(0)
	v_add_f32_e32 v32, v32, v33
	ds_bpermute_b32 v33, v183, v32
	v_pk_mul_f32 v[34:35], v[152:153], v[34:35]
	v_pk_mul_f32 v[36:37], v[154:155], v[36:37]
	v_cvt_pk_bf16_f32 v34, v34, v35
	s_nop 0
	v_cvt_pk_bf16_f32 v35, v36, v37
	global_store_dwordx2 v[52:53], v[34:35], off offset:288
	s_and_saveexec_b64 s[36:37], s[6:7]
	s_cbranch_execz .LBB0_548
	s_waitcnt lgkmcnt(0)
	v_add_f32_e32 v32, v32, v33
	ds_write_b32 v184, v32 offset:2304
; __device__ __forceinline__ unsigned cvt_pk_bf16(float lo, float hi) { unsigned r; asm volatile("v_cvt_pk_bf16_f32 %0, %1, %2" : "=v"(r) : "v"(lo), "v"(hi)); return r; }
; __device__ __forceinline__ float shx(float v, int o, int lane) { return __int_as_float(__builtin_amdgcn_ds_bpermute((lane ^ o) << 2, __float_as_int(v))); }
;     __device__ __forceinline__ void operator()(const f32x4 (&acc)[2][2][4][2], const Unit& u, int wr, int wc, int fr, int fq) const {
;     ...
;             for (int m = 0; m < 4; ++m) { const int row = row0 + ai * HALF + m * 16; const size_t off = (size_t)row * DM + col0; float ss = 0.f;
; #pragma unroll
;                 for (int bj = 0; bj < 2; ++bj)
; #pragma unroll
;                     for (int n = 0; n < 2; ++n) { const f32x4 x = *(const f32x4*)(src + off + bj * HALF + n * 16) + gv[bj][n] * acc[ai][bj][m][n];
;                         *(f32x4*)(dst + off + bj * HALF + n * 16) = x; ss += (x[0] * x[0] + x[1] * x[1]) + (x[2] * x[2] + x[3] * x[3]);
;                         const f32x4 hh = x * gs[bj][n]; u32x2 w; w.x = cvt_pk_bf16(hh[0], hh[1]); w.y = cvt_pk_bf16(hh[2], hh[3]); *(u32x2*)(Hn + off + bj * HALF + n * 16) = w; }
;                 ss += shx(ss, 16, lane); ss += shx(ss, 32, lane);
;                 if (fq == 0) scr[(ai * HALF + wr * 64 + m * 16 + fr) * 4 + wc] = ss; }
.LBB0_548:
	s_or_b64 exec, exec, s[36:37]
	s_waitcnt lgkmcnt(0)
	v_lshlrev_b64 v[32:33], 10, v[170:171]
	v_lshl_add_u64 v[32:33], v[32:33], 0, v[168:169]
	s_mov_b64 s[36:37], 0x28000
	v_lshl_add_u64 v[38:39], v[32:33], 0, s[36:37]
	v_lshlrev_b64 v[40:41], 2, v[38:39]
	v_lshl_add_u64 v[42:43], s[4:5], 0, v[40:41]
	v_lshl_add_u64 v[38:39], v[38:39], 1, s[18:19]
	v_lshl_add_u64 v[40:41], s[12:13], 0, v[40:41]
	s_waitcnt vmcnt(17)
	v_pk_fma_f32 v[28:29], v[28:29], v[88:89], v[196:197]
	v_pk_fma_f32 v[30:31], v[30:31], v[90:91], v[198:199]
	v_pk_mul_f32 v[36:37], v[166:167], v[28:29]
	global_store_dwordx4 v[40:41], v[28:31], off nt
	v_pk_mul_f32 v[34:35], v[164:165], v[30:31]
	v_cvt_pk_bf16_f32 v36, v36, v37
	s_nop 0
	v_cvt_pk_bf16_f32 v37, v34, v35
	global_store_dwordx2 v[38:39], v[36:37], off
	v_mul_f32_e32 v29, v29, v29
	v_mul_f32_e32 v31, v31, v31
	v_fmac_f32_e32 v29, v28, v28
	v_fmac_f32_e32 v31, v30, v30
	v_add_f32_e32 v28, v29, v31
	s_waitcnt vmcnt(18)
	v_pk_fma_f32 v[24:25], v[24:25], v[92:93], v[200:201]
	v_pk_fma_f32 v[26:27], v[26:27], v[94:95], v[202:203]
	v_pk_mul_f32 v[36:37], v[162:163], v[24:25]
	global_store_dwordx4 v[40:41], v[24:27], off offset:64 nt
	v_pk_mul_f32 v[34:35], v[160:161], v[26:27]
	v_cvt_pk_bf16_f32 v36, v36, v37
	s_nop 0
	v_cvt_pk_bf16_f32 v37, v34, v35
	global_store_dwordx2 v[38:39], v[36:37], off offset:32
	v_mul_f32_e32 v25, v25, v25
	v_mul_f32_e32 v27, v27, v27
	v_fmac_f32_e32 v25, v24, v24
	v_fmac_f32_e32 v27, v26, v26
	v_add_f32_e32 v24, v25, v27
	v_add_f32_e32 v24, v28, v24
	s_waitcnt vmcnt(19)
	v_pk_fma_f32 v[20:21], v[20:21], v[76:77], v[204:205]
	v_pk_fma_f32 v[22:23], v[22:23], v[78:79], v[206:207]
	v_pk_mul_f32 v[36:37], v[158:159], v[20:21]
	global_store_dwordx4 v[40:41], v[20:23], off offset:512 nt
	v_pk_mul_f32 v[34:35], v[156:157], v[22:23]
	v_cvt_pk_bf16_f32 v36, v36, v37
	s_nop 0
	v_cvt_pk_bf16_f32 v37, v34, v35
	global_store_dwordx2 v[38:39], v[36:37], off offset:256
	v_mul_f32_e32 v21, v21, v21
	v_mul_f32_e32 v23, v23, v23
	v_fmac_f32_e32 v21, v20, v20
	v_fmac_f32_e32 v23, v22, v22
	v_add_f32_e32 v20, v21, v23
	v_add_f32_e32 v22, v24, v20
	s_waitcnt vmcnt(20)
	v_pk_fma_f32 v[20:21], v[18:19], v[74:75], v[210:211]
	v_pk_fma_f32 v[18:19], v[16:17], v[72:73], v[208:209]
	v_mul_f32_e32 v17, v21, v21
	v_mul_f32_e32 v16, v19, v19
	v_fmac_f32_e32 v16, v18, v18
	v_fmac_f32_e32 v17, v20, v20
	v_add_f32_e32 v16, v16, v17
	v_add_f32_e32 v16, v22, v16
	ds_bpermute_b32 v17, v182, v16
	global_store_dwordx4 v[40:41], v[18:21], off offset:576 nt
	s_waitcnt lgkmcnt(0)
	v_add_f32_e32 v16, v16, v17
	ds_bpermute_b32 v17, v183, v16
	v_pk_mul_f32 v[18:19], v[152:153], v[18:19]
	v_pk_mul_f32 v[20:21], v[154:155], v[20:21]
	v_cvt_pk_bf16_f32 v18, v18, v19
	s_nop 0
	v_cvt_pk_bf16_f32 v19, v20, v21
	global_store_dwordx2 v[38:39], v[18:19], off offset:288
	s_and_saveexec_b64 s[36:37], s[6:7]
	s_cbranch_execz .LBB0_550
	s_waitcnt lgkmcnt(0)
	v_add_f32_e32 v16, v16, v17
	ds_write_b32 v184, v16 offset:2560
.LBB0_550:
	s_or_b64 exec, exec, s[36:37]
	s_mov_b64 s[36:37], 0x2c000
	v_lshl_add_u64 v[20:21], v[32:33], 0, s[36:37]
	v_lshlrev_b64 v[22:23], 2, v[20:21]
	v_lshl_add_u64 v[24:25], s[4:5], 0, v[22:23]
	s_waitcnt lgkmcnt(0)
	v_lshl_add_u64 v[20:21], v[20:21], 1, s[18:19]
	v_lshl_add_u64 v[22:23], s[12:13], 0, v[22:23]
	s_waitcnt vmcnt(13)
	v_pk_fma_f32 v[12:13], v[12:13], v[88:89], v[212:213]
	v_pk_fma_f32 v[14:15], v[14:15], v[90:91], v[214:215]
	v_pk_mul_f32 v[18:19], v[166:167], v[12:13]
	global_store_dwordx4 v[22:23], v[12:15], off nt
	v_pk_mul_f32 v[16:17], v[164:165], v[14:15]
	v_cvt_pk_bf16_f32 v18, v18, v19
	s_nop 0
	v_cvt_pk_bf16_f32 v19, v16, v17
	global_store_dwordx2 v[20:21], v[18:19], off
	v_mul_f32_e32 v13, v13, v13
	v_mul_f32_e32 v15, v15, v15
	v_fmac_f32_e32 v13, v12, v12
	v_fmac_f32_e32 v15, v14, v14
	v_add_f32_e32 v12, v13, v15
	s_waitcnt vmcnt(14)
	v_pk_fma_f32 v[8:9], v[8:9], v[92:93], v[216:217]
	v_pk_fma_f32 v[10:11], v[10:11], v[94:95], v[218:219]
	v_pk_mul_f32 v[18:19], v[162:163], v[8:9]
	global_store_dwordx4 v[22:23], v[8:11], off offset:64 nt
	v_pk_mul_f32 v[16:17], v[160:161], v[10:11]
	v_cvt_pk_bf16_f32 v18, v18, v19
	s_nop 0
	v_cvt_pk_bf16_f32 v19, v16, v17
	global_store_dwordx2 v[20:21], v[18:19], off offset:32
	v_mul_f32_e32 v9, v9, v9
	v_mul_f32_e32 v11, v11, v11
	v_fmac_f32_e32 v9, v8, v8
	v_fmac_f32_e32 v11, v10, v10
	v_add_f32_e32 v8, v9, v11
	v_add_f32_e32 v8, v12, v8
	s_waitcnt vmcnt(15)
	v_pk_fma_f32 v[4:5], v[4:5], v[76:77], v[220:221]
	v_pk_fma_f32 v[6:7], v[6:7], v[78:79], v[222:223]
	v_pk_mul_f32 v[18:19], v[158:159], v[4:5]
	global_store_dwordx4 v[22:23], v[4:7], off offset:512 nt
	v_pk_mul_f32 v[16:17], v[156:157], v[6:7]
	v_cvt_pk_bf16_f32 v18, v18, v19
	s_nop 0
	v_cvt_pk_bf16_f32 v19, v16, v17
	global_store_dwordx2 v[20:21], v[18:19], off offset:256
	v_mul_f32_e32 v5, v5, v5
	v_mul_f32_e32 v7, v7, v7
	v_fmac_f32_e32 v5, v4, v4
	v_fmac_f32_e32 v7, v6, v6
	v_add_f32_e32 v4, v5, v7
	v_add_f32_e32 v6, v8, v4
	s_waitcnt vmcnt(16)
	v_pk_fma_f32 v[4:5], v[2:3], v[74:75], v[226:227]
	v_pk_fma_f32 v[2:3], v[0:1], v[72:73], v[224:225]
	v_mul_f32_e32 v1, v5, v5
	v_mul_f32_e32 v0, v3, v3
	v_fmac_f32_e32 v0, v2, v2
	v_fmac_f32_e32 v1, v4, v4
	v_add_f32_e32 v0, v0, v1
	v_add_f32_e32 v0, v6, v0
	ds_bpermute_b32 v1, v182, v0
	global_store_dwordx4 v[22:23], v[2:5], off offset:576 nt
	s_waitcnt lgkmcnt(0)
	v_add_f32_e32 v0, v0, v1
	ds_bpermute_b32 v1, v183, v0
	v_pk_mul_f32 v[2:3], v[152:153], v[2:3]
	v_pk_mul_f32 v[4:5], v[154:155], v[4:5]
	v_cvt_pk_bf16_f32 v2, v2, v3
	s_nop 0
	v_cvt_pk_bf16_f32 v3, v4, v5
	global_store_dwordx2 v[20:21], v[2:3], off offset:288
	s_and_saveexec_b64 s[36:37], s[6:7]
	s_cbranch_execz .LBB0_552
	s_waitcnt lgkmcnt(0)
	v_add_f32_e32 v0, v0, v1
	ds_write_b32 v184, v0 offset:2816

; __device__ __forceinline__ unsigned cvt_pk_bf16(float lo, float hi) { unsigned r; asm volatile("v_cvt_pk_bf16_f32 %0, %1, %2" : "=v"(r) : "v"(lo), "v"(hi)); return r; }
; __device__ __forceinline__ float shx(float v, int o, int lane) { return __int_as_float(__builtin_amdgcn_ds_bpermute((lane ^ o) << 2, __float_as_int(v))); }
;     __device__ __forceinline__ void operator()(const f32x4 (&acc)[2][2][4][2], const Unit& u, int wr, int wc, int fr, int fq) const {
;         const int bidx = u.pm >> 4, row0 = u.pm * BM + wr * 64 + fr, col0 = u.pn * BM + wc * 32 + 4 * fq, lane = fq * 16 + fr;
;         f32x4 gv[2][2], gs[2][2];
; #pragma unroll
;         for (int bj = 0; bj < 2; ++bj)
; #pragma unroll
;             for (int n = 0; n < 2; ++n) { const int c = col0 + bj * HALF + n * 16; gv[bj][n] = *(const f32x4*)(gate + (size_t)bidx * NMOD + c);
;                 gs[bj][n] = *(const f32x4*)(gnext + c) * (*(const f32x4*)(scn + (size_t)bidx * NMOD + c) + 1.0f); }
; #pragma unroll
;         for (int ai = 0; ai < 2; ++ai)
; #pragma unroll
;             for (int m = 0; m < 4; ++m) { const int row = row0 + ai * HALF + m * 16; const size_t off = (size_t)row * DM + col0; float ss = 0.f;
; #pragma unroll
;                 for (int bj = 0; bj < 2; ++bj)
; #pragma unroll
;                     for (int n = 0; n < 2; ++n) { const f32x4 x = *(const f32x4*)(src + off + bj * HALF + n * 16) + gv[bj][n] * acc[ai][bj][m][n];
;                         *(f32x4*)(dst + off + bj * HALF + n * 16) = x; ss += (x[0] * x[0] + x[1] * x[1]) + (x[2] * x[2] + x[3] * x[3]);
;                         const f32x4 hh = x * gs[bj][n]; u32x2 w; w.x = cvt_pk_bf16(hh[0], hh[1]); w.y = cvt_pk_bf16(hh[2], hh[3]); *(u32x2*)(Hn + off + bj * HALF + n * 16) = w; }
;                 ss += shx(ss, 16, lane); ss += shx(ss, 32, lane);
;                 if (fq == 0) scr[(ai * HALF + wr * 64 + m * 16 + fr) * 4 + wc] = ss; }
.LBB0_1578:
	s_ashr_i32 s25, s34, 4
	s_lshl_b32 s34, s34, 8
	s_mul_hi_i32 s27, s25, 0x6000
	s_mulk_i32 s25, 0x6000
	v_lshl_or_b32 v168, s36, 8, v185
	s_add_u32 s36, s55, s25
	s_addc_u32 s37, s56, s27
	s_add_u32 s38, s57, s25
	v_ashrrev_i32_e32 v169, 31, v168
	s_addc_u32 s39, s58, s27
	v_lshlrev_b64 v[76:77], 2, v[168:169]
	v_lshl_add_u64 v[176:177], s[38:39], 0, v[76:77]
	v_lshl_add_u64 v[170:171], s[36:37], 0, v[76:77]
	v_lshl_add_u64 v[174:175], s[20:21], 0, v[76:77]
	global_load_dwordx4 v[76:79], v[176:177], off
	global_load_dwordx4 v[72:75], v[174:175], off
	global_load_dwordx4 v[88:91], v[170:171], off
	s_waitcnt vmcnt(0)
	v_pk_add_f32 v[78:79], v[78:79], 1.0 op_sel_hi:[1,0]
	v_pk_add_f32 v[76:77], v[76:77], 1.0 op_sel_hi:[1,0]
	v_pk_mul_f32 v[164:165], v[74:75], v[78:79]
	v_pk_mul_f32 v[166:167], v[72:73], v[76:77]
	global_load_dwordx4 v[92:95], v[170:171], off offset:64
	global_load_dwordx4 v[72:75], v[174:175], off offset:64
	global_load_dwordx4 v[76:79], v[176:177], off offset:64
	s_waitcnt vmcnt(0)
	v_pk_add_f32 v[78:79], v[78:79], 1.0 op_sel_hi:[1,0]
	v_pk_add_f32 v[76:77], v[76:77], 1.0 op_sel_hi:[1,0]
	v_pk_mul_f32 v[160:161], v[74:75], v[78:79]
	v_pk_mul_f32 v[162:163], v[72:73], v[76:77]
	global_load_dwordx4 v[76:79], v[170:171], off offset:512
	global_load_dwordx4 v[72:75], v[174:175], off offset:512
	global_load_dwordx4 v[152:155], v[176:177], off offset:512
	s_waitcnt vmcnt(0)
	v_pk_add_f32 v[154:155], v[154:155], 1.0 op_sel_hi:[1,0]
	v_pk_add_f32 v[152:153], v[152:153], 1.0 op_sel_hi:[1,0]
	v_pk_mul_f32 v[156:157], v[74:75], v[154:155]
	v_pk_mul_f32 v[158:159], v[72:73], v[152:153]
	global_load_dwordx4 v[72:75], v[170:171], off offset:576
	global_load_dwordx4 v[152:155], v[174:175], off offset:576
	s_nop 0
	global_load_dwordx4 v[174:177], v[176:177], off offset:576
	s_waitcnt vmcnt(0)
	v_pk_add_f32 v[170:171], v[176:177], 1.0 op_sel_hi:[1,0]
	s_nop 0
	v_pk_mul_f32 v[154:155], v[154:155], v[170:171]
	v_add_u32_e32 v170, s34, v180
	v_pk_add_f32 v[174:175], v[174:175], 1.0 op_sel_hi:[1,0]
	v_ashrrev_i32_e32 v171, 31, v170
	v_pk_mul_f32 v[152:153], v[152:153], v[174:175]
	v_lshlrev_b64 v[174:175], 10, v[170:171]
	v_lshl_add_u64 v[192:193], v[174:175], 0, v[168:169]
	v_lshlrev_b64 v[194:195], 2, v[192:193]
	v_lshl_add_u64 v[178:179], s[4:5], 0, v[194:195]
	v_mov_b32_e32 v228, v194
	v_mov_b32_e32 v229, v228
	global_load_dwordx4 v[196:199], v229, s[4:5] nt
	global_load_dwordx4 v[200:203], v229, s[4:5] offset:64 nt
	global_load_dwordx4 v[204:207], v229, s[4:5] offset:512 nt
	global_load_dwordx4 v[208:211], v229, s[4:5] offset:576 nt
	v_add_u32_e32 v229, 0x10000, v228
	global_load_dwordx4 v[212:215], v229, s[4:5] nt
	global_load_dwordx4 v[216:219], v229, s[4:5] offset:64 nt
	global_load_dwordx4 v[220:223], v229, s[4:5] offset:512 nt
	global_load_dwordx4 v[224:227], v229, s[4:5] offset:576 nt
	s_waitcnt vmcnt(7)
	v_pk_fma_f32 v[176:177], v[142:143], v[90:91], v[198:199]
	v_pk_fma_f32 v[174:175], v[140:141], v[88:89], v[196:197]
	v_mul_f32_e32 v143, v177, v177
	v_mul_f32_e32 v142, v175, v175
	v_lshl_add_u64 v[140:141], s[12:13], 0, v[194:195]
	v_fmac_f32_e32 v142, v174, v174
	v_fmac_f32_e32 v143, v176, v176
	global_store_dwordx4 v[140:141], v[174:177], off nt
	v_add_f32_e32 v194, v142, v143
	v_pk_mul_f32 v[142:143], v[164:165], v[176:177]
	v_pk_mul_f32 v[174:175], v[166:167], v[174:175]
	s_nop 0
	v_cvt_pk_bf16_f32 v174, v174, v175
	v_cvt_pk_bf16_f32 v175, v142, v143
	v_lshl_add_u64 v[142:143], v[192:193], 1, s[18:19]
	global_store_dwordx2 v[142:143], v[174:175], off
	s_waitcnt vmcnt(8)
	v_pk_fma_f32 v[136:137], v[136:137], v[92:93], v[200:201]
	v_pk_fma_f32 v[138:139], v[138:139], v[94:95], v[202:203]
	v_mul_f32_e32 v174, v137, v137
	global_store_dwordx4 v[140:141], v[136:139], off offset:64 nt
	v_fmac_f32_e32 v174, v136, v136
	v_mul_f32_e32 v175, v139, v139
	v_pk_mul_f32 v[136:137], v[162:163], v[136:137]
	v_fmac_f32_e32 v175, v138, v138
	v_pk_mul_f32 v[138:139], v[160:161], v[138:139]
	v_cvt_pk_bf16_f32 v136, v136, v137
	v_add_f32_e32 v174, v174, v175
	v_cvt_pk_bf16_f32 v137, v138, v139
	global_store_dwordx2 v[142:143], v[136:137], off offset:32
	v_add_f32_e32 v174, v194, v174
	s_waitcnt vmcnt(9)
	v_pk_fma_f32 v[132:133], v[132:133], v[76:77], v[204:205]
	v_pk_fma_f32 v[134:135], v[134:135], v[78:79], v[206:207]
	v_mul_f32_e32 v136, v133, v133
	global_store_dwordx4 v[140:141], v[132:135], off offset:512 nt
	v_fmac_f32_e32 v136, v132, v132
	v_mul_f32_e32 v137, v135, v135
	v_pk_mul_f32 v[132:133], v[158:159], v[132:133]
	v_fmac_f32_e32 v137, v134, v134
	v_pk_mul_f32 v[134:135], v[156:157], v[134:135]
	v_cvt_pk_bf16_f32 v132, v132, v133
	v_add_f32_e32 v136, v136, v137
	v_cvt_pk_bf16_f32 v133, v134, v135
	global_store_dwordx2 v[142:143], v[132:133], off offset:256
	v_add_f32_e32 v136, v174, v136
	s_waitcnt vmcnt(10)
	v_pk_fma_f32 v[130:131], v[130:131], v[74:75], v[210:211]
	v_pk_fma_f32 v[128:129], v[128:129], v[72:73], v[208:209]
	v_add_u32_e32 v229, 0x20000, v228
	global_load_dwordx4 v[196:199], v229, s[4:5] nt
	global_load_dwordx4 v[200:203], v229, s[4:5] offset:64 nt
	global_load_dwordx4 v[204:207], v229, s[4:5] offset:512 nt
	global_load_dwordx4 v[208:211], v229, s[4:5] offset:576 nt
	v_mul_f32_e32 v133, v131, v131
	v_mul_f32_e32 v132, v129, v129
	v_fmac_f32_e32 v132, v128, v128
	v_fmac_f32_e32 v133, v130, v130
	global_store_dwordx4 v[140:141], v[128:131], off offset:576 nt
	v_add_f32_e32 v132, v132, v133
	v_add_f32_e32 v132, v136, v132
	v_pk_mul_f32 v[128:129], v[152:153], v[128:129]
	v_pk_mul_f32 v[130:131], v[154:155], v[130:131]
	v_cvt_pk_bf16_f32 v128, v128, v129
	s_nop 0
	v_cvt_pk_bf16_f32 v129, v130, v131
	global_store_dwordx2 v[142:143], v[128:129], off offset:288
	ds_bpermute_b32 v128, v182, v132
	s_waitcnt lgkmcnt(0)
	v_add_f32_e32 v128, v132, v128
	ds_bpermute_b32 v129, v183, v128
	s_and_saveexec_b64 s[36:37], s[6:7]
	s_cbranch_execz .LBB0_1580
	s_waitcnt lgkmcnt(0)
	v_add_f32_e32 v128, v128, v129
	ds_write_b32 v184, v128

; __device__ __forceinline__ unsigned cvt_pk_bf16(float lo, float hi) { unsigned r; asm volatile("v_cvt_pk_bf16_f32 %0, %1, %2" : "=v"(r) : "v"(lo), "v"(hi)); return r; }
; __device__ __forceinline__ float shx(float v, int o, int lane) { return __int_as_float(__builtin_amdgcn_ds_bpermute((lane ^ o) << 2, __float_as_int(v))); }
;     __device__ __forceinline__ void operator()(const f32x4 (&acc)[2][2][4][2], const Unit& u, int wr, int wc, int fr, int fq) const {
;         const int bidx = u.pm >> 4, row0 = u.pm * BM + wr * 64 + fr, col0 = u.pn * BM + wc * 32 + 4 * fq, lane = fq * 16 + fr;
;         f32x4 gv[2][2], gs[2][2];
; #pragma unroll
;         for (int bj = 0; bj < 2; ++bj)
; #pragma unroll
;             for (int n = 0; n < 2; ++n) { const int c = col0 + bj * HALF + n * 16; gv[bj][n] = *(const f32x4*)(gate + (size_t)bidx * NMOD + c);
;                 gs[bj][n] = *(const f32x4*)(gnext + c) * (*(const f32x4*)(scn + (size_t)bidx * NMOD + c) + 1.0f); }
; #pragma unroll
;         for (int ai = 0; ai < 2; ++ai)
; #pragma unroll
;             for (int m = 0; m < 4; ++m) { const int row = row0 + ai * HALF + m * 16; const size_t off = (size_t)row * DM + col0; float ss = 0.f;
; #pragma unroll
;                 for (int bj = 0; bj < 2; ++bj)
; #pragma unroll
;                     for (int n = 0; n < 2; ++n) { const f32x4 x = *(const f32x4*)(src + off + bj * HALF + n * 16) + gv[bj][n] * acc[ai][bj][m][n];
;                         *(f32x4*)(dst + off + bj * HALF + n * 16) = x; ss += (x[0] * x[0] + x[1] * x[1]) + (x[2] * x[2] + x[3] * x[3]);
;                         const f32x4 hh = x * gs[bj][n]; u32x2 w; w.x = cvt_pk_bf16(hh[0], hh[1]); w.y = cvt_pk_bf16(hh[2], hh[3]); *(u32x2*)(Hn + off + bj * HALF + n * 16) = w; }
;                 ss += shx(ss, 16, lane); ss += shx(ss, 32, lane);
;                 if (fq == 0) scr[(ai * HALF + wr * 64 + m * 16 + fr) * 4 + wc] = ss; }
.LBB0_1909:
	s_ashr_i32 s25, s34, 4
	s_lshl_b32 s34, s34, 8
	s_mul_hi_i32 s27, s25, 0x6000
	s_mulk_i32 s25, 0x6000
	v_lshl_or_b32 v168, s36, 8, v185
	s_add_u32 s36, s58, s25
	s_addc_u32 s37, s59, s27
	s_add_u32 s38, s60, s25
	v_ashrrev_i32_e32 v169, 31, v168
	s_addc_u32 s39, s61, s27
	v_lshlrev_b64 v[80:81], 2, v[168:169]
	v_lshl_add_u64 v[176:177], s[38:39], 0, v[80:81]
	v_lshl_add_u64 v[170:171], s[36:37], 0, v[80:81]
	v_lshl_add_u64 v[174:175], s[20:21], 0, v[80:81]
	global_load_dwordx4 v[80:83], v[176:177], off
	global_load_dwordx4 v[72:75], v[174:175], off
	global_load_dwordx4 v[92:95], v[170:171], off
	s_waitcnt vmcnt(0)
	v_pk_add_f32 v[82:83], v[82:83], 1.0 op_sel_hi:[1,0]
	v_pk_add_f32 v[80:81], v[80:81], 1.0 op_sel_hi:[1,0]
	v_pk_mul_f32 v[164:165], v[74:75], v[82:83]
	v_pk_mul_f32 v[166:167], v[72:73], v[80:81]
	global_load_dwordx4 v[88:91], v[170:171], off offset:64
	global_load_dwordx4 v[72:75], v[174:175], off offset:64
	global_load_dwordx4 v[80:83], v[176:177], off offset:64
	s_waitcnt vmcnt(0)
	v_pk_add_f32 v[82:83], v[82:83], 1.0 op_sel_hi:[1,0]
	v_pk_add_f32 v[80:81], v[80:81], 1.0 op_sel_hi:[1,0]
	v_pk_mul_f32 v[160:161], v[74:75], v[82:83]
	v_pk_mul_f32 v[162:163], v[72:73], v[80:81]
	global_load_dwordx4 v[80:83], v[170:171], off offset:512
	global_load_dwordx4 v[72:75], v[174:175], off offset:512
	global_load_dwordx4 v[152:155], v[176:177], off offset:512
	s_waitcnt vmcnt(0)
	v_pk_add_f32 v[154:155], v[154:155], 1.0 op_sel_hi:[1,0]
	v_pk_add_f32 v[152:153], v[152:153], 1.0 op_sel_hi:[1,0]
	v_pk_mul_f32 v[156:157], v[74:75], v[154:155]
	v_pk_mul_f32 v[158:159], v[72:73], v[152:153]
	global_load_dwordx4 v[72:75], v[170:171], off offset:576
	global_load_dwordx4 v[152:155], v[174:175], off offset:576
	s_nop 0
	global_load_dwordx4 v[174:177], v[176:177], off offset:576
	s_waitcnt vmcnt(0)
	v_pk_add_f32 v[170:171], v[176:177], 1.0 op_sel_hi:[1,0]
	s_nop 0
	v_pk_mul_f32 v[154:155], v[154:155], v[170:171]
	v_add_u32_e32 v170, s34, v180
	v_pk_add_f32 v[174:175], v[174:175], 1.0 op_sel_hi:[1,0]
	v_ashrrev_i32_e32 v171, 31, v170
	v_pk_mul_f32 v[152:153], v[152:153], v[174:175]
	v_lshlrev_b64 v[174:175], 10, v[170:171]
	v_lshl_add_u64 v[192:193], v[174:175], 0, v[168:169]
	v_lshl_add_u64 v[178:179], v[192:193], 2, s[16:17]
	v_lshlrev_b32_e32 v228, 2, v192
	v_mov_b32_e32 v229, v228
	global_load_dwordx4 v[196:199], v229, s[16:17] nt
	global_load_dwordx4 v[200:203], v229, s[16:17] offset:64 nt
	global_load_dwordx4 v[204:207], v229, s[16:17] offset:512 nt
	global_load_dwordx4 v[208:211], v229, s[16:17] offset:576 nt
	v_add_u32_e32 v229, 0x10000, v228
	global_load_dwordx4 v[212:215], v229, s[16:17] nt
	global_load_dwordx4 v[216:219], v229, s[16:17] offset:64 nt
	global_load_dwordx4 v[220:223], v229, s[16:17] offset:512 nt
	global_load_dwordx4 v[224:227], v229, s[16:17] offset:576 nt
	s_waitcnt vmcnt(7)
	v_pk_fma_f32 v[142:143], v[142:143], v[94:95], v[198:199]
	v_pk_fma_f32 v[140:141], v[140:141], v[92:93], v[196:197]
	v_mul_f32_e32 v175, v143, v143
	v_mul_f32_e32 v174, v141, v141
	global_store_dwordx4 v[178:179], v[140:143], off nt
	v_fmac_f32_e32 v174, v140, v140
	v_fmac_f32_e32 v175, v142, v142
	v_pk_mul_f32 v[140:141], v[166:167], v[140:141]
	v_add_f32_e32 v194, v174, v175
	v_cvt_pk_bf16_f32 v174, v140, v141
	v_lshl_add_u64 v[140:141], v[192:193], 1, s[14:15]
	v_pk_mul_f32 v[142:143], v[164:165], v[142:143]
	s_nop 0
	v_cvt_pk_bf16_f32 v175, v142, v143
	global_store_dwordx2 v[140:141], v[174:175], off
	s_waitcnt vmcnt(8)
	v_pk_fma_f32 v[136:137], v[136:137], v[88:89], v[200:201]
	v_pk_fma_f32 v[138:139], v[138:139], v[90:91], v[202:203]
	v_mul_f32_e32 v142, v137, v137
	global_store_dwordx4 v[178:179], v[136:139], off offset:64 nt
	v_fmac_f32_e32 v142, v136, v136
	v_mul_f32_e32 v143, v139, v139
	v_pk_mul_f32 v[136:137], v[162:163], v[136:137]
	v_fmac_f32_e32 v143, v138, v138
	v_pk_mul_f32 v[138:139], v[160:161], v[138:139]
	v_cvt_pk_bf16_f32 v136, v136, v137
	v_add_f32_e32 v142, v142, v143
	v_cvt_pk_bf16_f32 v137, v138, v139
	global_store_dwordx2 v[140:141], v[136:137], off offset:32
	v_add_f32_e32 v142, v194, v142
	s_waitcnt vmcnt(9)
	v_pk_fma_f32 v[132:133], v[132:133], v[80:81], v[204:205]
	v_pk_fma_f32 v[134:135], v[134:135], v[82:83], v[206:207]
	v_mul_f32_e32 v136, v133, v133
	global_store_dwordx4 v[178:179], v[132:135], off offset:512 nt
	v_fmac_f32_e32 v136, v132, v132
	v_mul_f32_e32 v137, v135, v135
	v_pk_mul_f32 v[132:133], v[158:159], v[132:133]
	v_fmac_f32_e32 v137, v134, v134
	v_pk_mul_f32 v[134:135], v[156:157], v[134:135]
	v_cvt_pk_bf16_f32 v132, v132, v133
	v_add_f32_e32 v136, v136, v137
	v_cvt_pk_bf16_f32 v133, v134, v135
	global_store_dwordx2 v[140:141], v[132:133], off offset:256
	v_add_f32_e32 v136, v142, v136
	s_waitcnt vmcnt(10)
	v_pk_fma_f32 v[130:131], v[130:131], v[74:75], v[210:211]
	v_pk_fma_f32 v[128:129], v[128:129], v[72:73], v[208:209]
	v_add_u32_e32 v229, 0x20000, v228
	global_load_dwordx4 v[196:199], v229, s[16:17] nt
	global_load_dwordx4 v[200:203], v229, s[16:17] offset:64 nt
	global_load_dwordx4 v[204:207], v229, s[16:17] offset:512 nt
	global_load_dwordx4 v[208:211], v229, s[16:17] offset:576 nt
	v_mul_f32_e32 v133, v131, v131
	v_mul_f32_e32 v132, v129, v129
	v_fmac_f32_e32 v132, v128, v128
	v_fmac_f32_e32 v133, v130, v130
	global_store_dwordx4 v[178:179], v[128:131], off offset:576 nt
	v_add_f32_e32 v132, v132, v133
	v_add_f32_e32 v132, v136, v132
	v_pk_mul_f32 v[128:129], v[152:153], v[128:129]
	v_pk_mul_f32 v[130:131], v[154:155], v[130:131]
	v_cvt_pk_bf16_f32 v128, v128, v129
	s_nop 0
	v_cvt_pk_bf16_f32 v129, v130, v131
	global_store_dwordx2 v[140:141], v[128:129], off offset:288
	ds_bpermute_b32 v128, v182, v132
	s_waitcnt lgkmcnt(0)
	v_add_f32_e32 v128, v132, v128
	ds_bpermute_b32 v129, v183, v128
	s_and_saveexec_b64 s[36:37], s[8:9]
	s_mov_b32 s70, 0xbf3a00e3
	s_cbranch_execz .LBB0_1911
	s_waitcnt lgkmcnt(0)
	v_add_f32_e32 v128, v128, v129
	ds_write_b32 v184, v128
; __device__ __forceinline__ unsigned cvt_pk_bf16(float lo, float hi) { unsigned r; asm volatile("v_cvt_pk_bf16_f32 %0, %1, %2" : "=v"(r) : "v"(lo), "v"(hi)); return r; }
; __device__ __forceinline__ float shx(float v, int o, int lane) { return __int_as_float(__builtin_amdgcn_ds_bpermute((lane ^ o) << 2, __float_as_int(v))); }
;     __device__ __forceinline__ void operator()(const f32x4 (&acc)[2][2][4][2], const Unit& u, int wr, int wc, int fr, int fq) const {
;     ...
;             for (int m = 0; m < 4; ++m) { const int row = row0 + ai * HALF + m * 16; const size_t off = (size_t)row * DM + col0; float ss = 0.f;
; #pragma unroll
;                 for (int bj = 0; bj < 2; ++bj)
; #pragma unroll
;                     for (int n = 0; n < 2; ++n) { const f32x4 x = *(const f32x4*)(src + off + bj * HALF + n * 16) + gv[bj][n] * acc[ai][bj][m][n];
;                         *(f32x4*)(dst + off + bj * HALF + n * 16) = x; ss += (x[0] * x[0] + x[1] * x[1]) + (x[2] * x[2] + x[3] * x[3]);
;                         const f32x4 hh = x * gs[bj][n]; u32x2 w; w.x = cvt_pk_bf16(hh[0], hh[1]); w.y = cvt_pk_bf16(hh[2], hh[3]); *(u32x2*)(Hn + off + bj * HALF + n * 16) = w; }
;                 ss += shx(ss, 16, lane); ss += shx(ss, 32, lane);
;                 if (fq == 0) scr[(ai * HALF + wr * 64 + m * 16 + fr) * 4 + wc] = ss; }
.LBB0_1911:
	s_or_b64 exec, exec, s[36:37]
	v_or_b32_e32 v128, 16, v170
	s_waitcnt lgkmcnt(0)
	v_ashrrev_i32_e32 v129, 31, v128
	v_lshlrev_b64 v[128:129], 10, v[128:129]
	v_lshl_add_u64 v[132:133], v[128:129], 0, v[168:169]
	v_lshl_add_u64 v[134:135], v[132:133], 2, s[16:17]
	v_lshl_add_u64 v[132:133], v[132:133], 1, s[14:15]
	s_waitcnt vmcnt(15)
	v_pk_fma_f32 v[124:125], v[124:125], v[92:93], v[212:213]
	v_pk_fma_f32 v[126:127], v[126:127], v[94:95], v[214:215]
	v_pk_mul_f32 v[130:131], v[166:167], v[124:125]
	global_store_dwordx4 v[134:135], v[124:127], off nt
	v_pk_mul_f32 v[128:129], v[164:165], v[126:127]
	v_cvt_pk_bf16_f32 v130, v130, v131
	s_nop 0
	v_cvt_pk_bf16_f32 v131, v128, v129
	global_store_dwordx2 v[132:133], v[130:131], off
	v_mul_f32_e32 v125, v125, v125
	v_mul_f32_e32 v127, v127, v127
	v_fmac_f32_e32 v125, v124, v124
	v_fmac_f32_e32 v127, v126, v126
	v_add_f32_e32 v124, v125, v127
	s_waitcnt vmcnt(16)
	v_pk_fma_f32 v[120:121], v[120:121], v[88:89], v[216:217]
	v_pk_fma_f32 v[122:123], v[122:123], v[90:91], v[218:219]
	v_pk_mul_f32 v[130:131], v[162:163], v[120:121]
	global_store_dwordx4 v[134:135], v[120:123], off offset:64 nt
	v_pk_mul_f32 v[128:129], v[160:161], v[122:123]
	v_cvt_pk_bf16_f32 v130, v130, v131
	s_nop 0
	v_cvt_pk_bf16_f32 v131, v128, v129
	global_store_dwordx2 v[132:133], v[130:131], off offset:32
	v_mul_f32_e32 v121, v121, v121
	v_mul_f32_e32 v123, v123, v123
	v_fmac_f32_e32 v121, v120, v120
	v_fmac_f32_e32 v123, v122, v122
	v_add_f32_e32 v120, v121, v123
	v_add_f32_e32 v120, v124, v120
	s_waitcnt vmcnt(17)
	v_pk_fma_f32 v[116:117], v[116:117], v[80:81], v[220:221]
	v_pk_fma_f32 v[118:119], v[118:119], v[82:83], v[222:223]
	v_pk_mul_f32 v[130:131], v[158:159], v[116:117]
	global_store_dwordx4 v[134:135], v[116:119], off offset:512 nt
	v_pk_mul_f32 v[128:129], v[156:157], v[118:119]
	v_cvt_pk_bf16_f32 v130, v130, v131
	s_nop 0
	v_cvt_pk_bf16_f32 v131, v128, v129
	global_store_dwordx2 v[132:133], v[130:131], off offset:256
	v_mul_f32_e32 v117, v117, v117
	v_mul_f32_e32 v119, v119, v119
	v_fmac_f32_e32 v117, v116, v116
	v_fmac_f32_e32 v119, v118, v118
	v_add_f32_e32 v116, v117, v119
	v_add_f32_e32 v118, v120, v116
	s_waitcnt vmcnt(18)
	v_pk_fma_f32 v[116:117], v[114:115], v[74:75], v[226:227]
	v_pk_fma_f32 v[114:115], v[112:113], v[72:73], v[224:225]
	v_add_u32_e32 v229, 0x30000, v228
	global_load_dwordx4 v[212:215], v229, s[16:17] nt
	global_load_dwordx4 v[216:219], v229, s[16:17] offset:64 nt
	global_load_dwordx4 v[220:223], v229, s[16:17] offset:512 nt
	global_load_dwordx4 v[224:227], v229, s[16:17] offset:576 nt
	v_mul_f32_e32 v113, v117, v117
	v_mul_f32_e32 v112, v115, v115
	v_fmac_f32_e32 v112, v114, v114
	v_fmac_f32_e32 v113, v116, v116
	v_add_f32_e32 v112, v112, v113
	v_add_f32_e32 v112, v118, v112
	ds_bpermute_b32 v113, v182, v112
	global_store_dwordx4 v[134:135], v[114:117], off offset:576 nt
	s_waitcnt lgkmcnt(0)
	v_add_f32_e32 v112, v112, v113
	ds_bpermute_b32 v113, v183, v112
	v_pk_mul_f32 v[114:115], v[152:153], v[114:115]
	v_pk_mul_f32 v[116:117], v[154:155], v[116:117]
	v_cvt_pk_bf16_f32 v114, v114, v115
	s_nop 0
	v_cvt_pk_bf16_f32 v115, v116, v117
	global_store_dwordx2 v[132:133], v[114:115], off offset:288
	s_and_saveexec_b64 s[36:37], s[8:9]
	s_cbranch_execz .LBB0_1913
	s_waitcnt lgkmcnt(0)
	v_add_f32_e32 v112, v112, v113
	ds_write_b32 v184, v112 offset:256
.LBB0_1913:
	s_or_b64 exec, exec, s[36:37]
	v_or_b32_e32 v112, 32, v170
	s_waitcnt lgkmcnt(0)
	v_ashrrev_i32_e32 v113, 31, v112
	v_lshlrev_b64 v[112:113], 10, v[112:113]
	v_lshl_add_u64 v[116:117], v[112:113], 0, v[168:169]
	v_lshl_add_u64 v[118:119], v[116:117], 2, s[16:17]
	v_lshl_add_u64 v[116:117], v[116:117], 1, s[14:15]
	s_waitcnt vmcnt(17)
	v_pk_fma_f32 v[108:109], v[108:109], v[92:93], v[196:197]
	v_pk_fma_f32 v[110:111], v[110:111], v[94:95], v[198:199]
	v_pk_mul_f32 v[114:115], v[166:167], v[108:109]
	global_store_dwordx4 v[118:119], v[108:111], off nt
	v_pk_mul_f32 v[112:113], v[164:165], v[110:111]
	v_cvt_pk_bf16_f32 v114, v114, v115
	s_nop 0
	v_cvt_pk_bf16_f32 v115, v112, v113
	global_store_dwordx2 v[116:117], v[114:115], off
	v_mul_f32_e32 v109, v109, v109
	v_mul_f32_e32 v111, v111, v111
	v_fmac_f32_e32 v109, v108, v108
	v_fmac_f32_e32 v111, v110, v110
	v_add_f32_e32 v108, v109, v111
	s_waitcnt vmcnt(18)
	v_pk_fma_f32 v[104:105], v[104:105], v[88:89], v[200:201]
	v_pk_fma_f32 v[106:107], v[106:107], v[90:91], v[202:203]
	v_pk_mul_f32 v[114:115], v[162:163], v[104:105]
	global_store_dwordx4 v[118:119], v[104:107], off offset:64 nt
	v_pk_mul_f32 v[112:113], v[160:161], v[106:107]
	v_cvt_pk_bf16_f32 v114, v114, v115
	s_nop 0
	v_cvt_pk_bf16_f32 v115, v112, v113
	global_store_dwordx2 v[116:117], v[114:115], off offset:32
	v_mul_f32_e32 v105, v105, v105
	v_mul_f32_e32 v107, v107, v107
	v_fmac_f32_e32 v105, v104, v104
	v_fmac_f32_e32 v107, v106, v106
	v_add_f32_e32 v104, v105, v107
	v_add_f32_e32 v104, v108, v104
	s_waitcnt vmcnt(19)
	v_pk_fma_f32 v[100:101], v[100:101], v[80:81], v[204:205]
	v_pk_fma_f32 v[102:103], v[102:103], v[82:83], v[206:207]
	v_pk_mul_f32 v[114:115], v[158:159], v[100:101]
	global_store_dwordx4 v[118:119], v[100:103], off offset:512 nt
	v_pk_mul_f32 v[112:113], v[156:157], v[102:103]
	v_cvt_pk_bf16_f32 v114, v114, v115
	s_nop 0
	v_cvt_pk_bf16_f32 v115, v112, v113
	global_store_dwordx2 v[116:117], v[114:115], off offset:256
	v_mul_f32_e32 v101, v101, v101
	v_mul_f32_e32 v103, v103, v103
	v_fmac_f32_e32 v101, v100, v100
	v_fmac_f32_e32 v103, v102, v102
	v_add_f32_e32 v100, v101, v103
	v_add_f32_e32 v102, v104, v100
	s_waitcnt vmcnt(20)
	v_pk_fma_f32 v[100:101], v[98:99], v[74:75], v[210:211]
	v_pk_fma_f32 v[98:99], v[96:97], v[72:73], v[208:209]
	v_add_u32_e32 v229, 0x80000, v228
	global_load_dwordx4 v[196:199], v229, s[16:17] nt
	global_load_dwordx4 v[200:203], v229, s[16:17] offset:64 nt
	global_load_dwordx4 v[204:207], v229, s[16:17] offset:512 nt
	global_load_dwordx4 v[208:211], v229, s[16:17] offset:576 nt
	v_mul_f32_e32 v97, v101, v101
	v_mul_f32_e32 v96, v99, v99
	v_fmac_f32_e32 v96, v98, v98
	v_fmac_f32_e32 v97, v100, v100
	v_add_f32_e32 v96, v96, v97
	v_add_f32_e32 v96, v102, v96
	ds_bpermute_b32 v97, v182, v96
	global_store_dwordx4 v[118:119], v[98:101], off offset:576 nt
	s_waitcnt lgkmcnt(0)
	v_add_f32_e32 v96, v96, v97
	ds_bpermute_b32 v97, v183, v96
	v_pk_mul_f32 v[98:99], v[152:153], v[98:99]
	v_pk_mul_f32 v[100:101], v[154:155], v[100:101]
	v_cvt_pk_bf16_f32 v98, v98, v99
	s_nop 0
	v_cvt_pk_bf16_f32 v99, v100, v101
	global_store_dwordx2 v[116:117], v[98:99], off offset:288
	s_and_saveexec_b64 s[36:37], s[8:9]
	s_cbranch_execz .LBB0_1915
	s_waitcnt lgkmcnt(0)
	v_add_f32_e32 v96, v96, v97
	ds_write_b32 v184, v96 offset:512
; __device__ __forceinline__ unsigned cvt_pk_bf16(float lo, float hi) { unsigned r; asm volatile("v_cvt_pk_bf16_f32 %0, %1, %2" : "=v"(r) : "v"(lo), "v"(hi)); return r; }
; __device__ __forceinline__ float shx(float v, int o, int lane) { return __int_as_float(__builtin_amdgcn_ds_bpermute((lane ^ o) << 2, __float_as_int(v))); }
;     __device__ __forceinline__ void operator()(const f32x4 (&acc)[2][2][4][2], const Unit& u, int wr, int wc, int fr, int fq) const {
;     ...
;             for (int m = 0; m < 4; ++m) { const int row = row0 + ai * HALF + m * 16; const size_t off = (size_t)row * DM + col0; float ss = 0.f;
; #pragma unroll
;                 for (int bj = 0; bj < 2; ++bj)
; #pragma unroll
;                     for (int n = 0; n < 2; ++n) { const f32x4 x = *(const f32x4*)(src + off + bj * HALF + n * 16) + gv[bj][n] * acc[ai][bj][m][n];
;                         *(f32x4*)(dst + off + bj * HALF + n * 16) = x; ss += (x[0] * x[0] + x[1] * x[1]) + (x[2] * x[2] + x[3] * x[3]);
;                         const f32x4 hh = x * gs[bj][n]; u32x2 w; w.x = cvt_pk_bf16(hh[0], hh[1]); w.y = cvt_pk_bf16(hh[2], hh[3]); *(u32x2*)(Hn + off + bj * HALF + n * 16) = w; }
;                 ss += shx(ss, 16, lane); ss += shx(ss, 32, lane);
;                 if (fq == 0) scr[(ai * HALF + wr * 64 + m * 16 + fr) * 4 + wc] = ss; }
.LBB0_1915:
	s_or_b64 exec, exec, s[36:37]
	v_or_b32_e32 v96, 48, v170
	s_waitcnt lgkmcnt(0)
	v_ashrrev_i32_e32 v97, 31, v96
	v_lshlrev_b64 v[96:97], 10, v[96:97]
	v_lshl_add_u64 v[100:101], v[96:97], 0, v[168:169]
	v_lshl_add_u64 v[102:103], v[100:101], 2, s[16:17]
	v_lshl_add_u64 v[100:101], v[100:101], 1, s[14:15]
	s_waitcnt vmcnt(17)
	v_pk_fma_f32 v[84:85], v[84:85], v[92:93], v[212:213]
	v_pk_fma_f32 v[86:87], v[86:87], v[94:95], v[214:215]
	v_pk_mul_f32 v[98:99], v[166:167], v[84:85]
	global_store_dwordx4 v[102:103], v[84:87], off nt
	v_pk_mul_f32 v[96:97], v[164:165], v[86:87]
	v_cvt_pk_bf16_f32 v98, v98, v99
	s_nop 0
	v_cvt_pk_bf16_f32 v99, v96, v97
	global_store_dwordx2 v[100:101], v[98:99], off
	v_mul_f32_e32 v85, v85, v85
	v_mul_f32_e32 v87, v87, v87
	v_fmac_f32_e32 v85, v84, v84
	v_fmac_f32_e32 v87, v86, v86
	v_add_f32_e32 v84, v85, v87
	s_waitcnt vmcnt(18)
	v_pk_fma_f32 v[76:77], v[76:77], v[88:89], v[216:217]
	v_pk_fma_f32 v[78:79], v[78:79], v[90:91], v[218:219]
	v_pk_mul_f32 v[98:99], v[162:163], v[76:77]
	global_store_dwordx4 v[102:103], v[76:79], off offset:64 nt
	v_pk_mul_f32 v[96:97], v[160:161], v[78:79]
	v_cvt_pk_bf16_f32 v98, v98, v99
	s_nop 0
	v_cvt_pk_bf16_f32 v99, v96, v97
	global_store_dwordx2 v[100:101], v[98:99], off offset:32
	v_mul_f32_e32 v77, v77, v77
	v_mul_f32_e32 v79, v79, v79
	v_fmac_f32_e32 v77, v76, v76
	v_fmac_f32_e32 v79, v78, v78
	v_add_f32_e32 v76, v77, v79
	v_add_f32_e32 v76, v84, v76
	s_waitcnt vmcnt(19)
	v_pk_fma_f32 v[68:69], v[68:69], v[80:81], v[220:221]
	v_pk_fma_f32 v[70:71], v[70:71], v[82:83], v[222:223]
	v_pk_mul_f32 v[98:99], v[158:159], v[68:69]
	global_store_dwordx4 v[102:103], v[68:71], off offset:512 nt
	v_pk_mul_f32 v[96:97], v[156:157], v[70:71]
	v_cvt_pk_bf16_f32 v98, v98, v99
	s_nop 0
	v_cvt_pk_bf16_f32 v99, v96, v97
	global_store_dwordx2 v[100:101], v[98:99], off offset:256
	v_mul_f32_e32 v69, v69, v69
	v_mul_f32_e32 v71, v71, v71
	v_fmac_f32_e32 v69, v68, v68
	v_fmac_f32_e32 v71, v70, v70
	v_add_f32_e32 v68, v69, v71
	v_add_f32_e32 v70, v76, v68
	s_waitcnt vmcnt(20)
	v_pk_fma_f32 v[68:69], v[66:67], v[74:75], v[226:227]
	v_pk_fma_f32 v[66:67], v[64:65], v[72:73], v[224:225]
	v_add_u32_e32 v229, 0x90000, v228
	global_load_dwordx4 v[212:215], v229, s[16:17] nt
	global_load_dwordx4 v[216:219], v229, s[16:17] offset:64 nt
	global_load_dwordx4 v[220:223], v229, s[16:17] offset:512 nt
	global_load_dwordx4 v[224:227], v229, s[16:17] offset:576 nt
	v_mul_f32_e32 v65, v69, v69
	v_mul_f32_e32 v64, v67, v67
	v_fmac_f32_e32 v64, v66, v66
	v_fmac_f32_e32 v65, v68, v68
	v_add_f32_e32 v64, v64, v65
	v_add_f32_e32 v64, v70, v64
	ds_bpermute_b32 v65, v182, v64
	global_store_dwordx4 v[102:103], v[66:69], off offset:576 nt
	s_waitcnt lgkmcnt(0)
	v_add_f32_e32 v64, v64, v65
	ds_bpermute_b32 v65, v183, v64
	v_pk_mul_f32 v[66:67], v[152:153], v[66:67]
	v_pk_mul_f32 v[68:69], v[154:155], v[68:69]
	v_cvt_pk_bf16_f32 v66, v66, v67
	s_nop 0
	v_cvt_pk_bf16_f32 v67, v68, v69
	global_store_dwordx2 v[100:101], v[66:67], off offset:288
	s_and_saveexec_b64 s[36:37], s[8:9]
	s_cbranch_execz .LBB0_1917
	s_waitcnt lgkmcnt(0)
	v_add_f32_e32 v64, v64, v65
	ds_write_b32 v184, v64 offset:768
.LBB0_1917:
	s_or_b64 exec, exec, s[36:37]
	s_waitcnt lgkmcnt(0)
	v_lshlrev_b64 v[64:65], 10, v[170:171]
	v_lshl_add_u64 v[64:65], v[64:65], 0, v[168:169]
	s_mov_b64 s[36:37], 0x20000
	v_lshl_add_u64 v[70:71], v[64:65], 0, s[36:37]
	v_lshl_add_u64 v[76:77], v[70:71], 2, s[16:17]
	v_lshl_add_u64 v[70:71], v[70:71], 1, s[14:15]
	s_waitcnt vmcnt(17)
	v_pk_fma_f32 v[60:61], v[60:61], v[92:93], v[196:197]
	v_pk_fma_f32 v[62:63], v[62:63], v[94:95], v[198:199]
	v_pk_mul_f32 v[68:69], v[166:167], v[60:61]
	global_store_dwordx4 v[76:77], v[60:63], off nt
	v_pk_mul_f32 v[66:67], v[164:165], v[62:63]
	v_cvt_pk_bf16_f32 v68, v68, v69
	s_nop 0
	v_cvt_pk_bf16_f32 v69, v66, v67
	global_store_dwordx2 v[70:71], v[68:69], off
	v_mul_f32_e32 v61, v61, v61
	v_mul_f32_e32 v63, v63, v63
	v_fmac_f32_e32 v61, v60, v60
	v_fmac_f32_e32 v63, v62, v62
	v_add_f32_e32 v60, v61, v63
	s_waitcnt vmcnt(18)
	v_pk_fma_f32 v[56:57], v[56:57], v[88:89], v[200:201]
	v_pk_fma_f32 v[58:59], v[58:59], v[90:91], v[202:203]
	v_pk_mul_f32 v[68:69], v[162:163], v[56:57]
	global_store_dwordx4 v[76:77], v[56:59], off offset:64 nt
	v_pk_mul_f32 v[66:67], v[160:161], v[58:59]
	v_cvt_pk_bf16_f32 v68, v68, v69
	s_nop 0
	v_cvt_pk_bf16_f32 v69, v66, v67
	global_store_dwordx2 v[70:71], v[68:69], off offset:32
	v_mul_f32_e32 v57, v57, v57
	v_mul_f32_e32 v59, v59, v59
	v_fmac_f32_e32 v57, v56, v56
	v_fmac_f32_e32 v59, v58, v58
	v_add_f32_e32 v56, v57, v59
	v_add_f32_e32 v56, v60, v56
	s_waitcnt vmcnt(19)
	v_pk_fma_f32 v[52:53], v[52:53], v[80:81], v[204:205]
	v_pk_fma_f32 v[54:55], v[54:55], v[82:83], v[206:207]
	v_pk_mul_f32 v[68:69], v[158:159], v[52:53]
	global_store_dwordx4 v[76:77], v[52:55], off offset:512 nt
	v_pk_mul_f32 v[66:67], v[156:157], v[54:55]
	v_cvt_pk_bf16_f32 v68, v68, v69
	s_nop 0
	v_cvt_pk_bf16_f32 v69, v66, v67
	global_store_dwordx2 v[70:71], v[68:69], off offset:256
	v_mul_f32_e32 v53, v53, v53
	v_mul_f32_e32 v55, v55, v55
	v_fmac_f32_e32 v53, v52, v52
	v_fmac_f32_e32 v55, v54, v54
	v_add_f32_e32 v52, v53, v55
	v_add_f32_e32 v54, v56, v52
	s_waitcnt vmcnt(20)
	v_pk_fma_f32 v[52:53], v[50:51], v[74:75], v[210:211]
	v_pk_fma_f32 v[50:51], v[48:49], v[72:73], v[208:209]
	v_add_u32_e32 v229, 0xa0000, v228
	global_load_dwordx4 v[196:199], v229, s[16:17] nt
	global_load_dwordx4 v[200:203], v229, s[16:17] offset:64 nt
	global_load_dwordx4 v[204:207], v229, s[16:17] offset:512 nt
	global_load_dwordx4 v[208:211], v229, s[16:17] offset:576 nt
	v_mul_f32_e32 v49, v53, v53
	v_mul_f32_e32 v48, v51, v51
	v_fmac_f32_e32 v48, v50, v50
	v_fmac_f32_e32 v49, v52, v52
	v_add_f32_e32 v48, v48, v49
	v_add_f32_e32 v48, v54, v48
	ds_bpermute_b32 v49, v182, v48
	global_store_dwordx4 v[76:77], v[50:53], off offset:576 nt
	s_waitcnt lgkmcnt(0)
	v_add_f32_e32 v48, v48, v49
	ds_bpermute_b32 v49, v183, v48
	v_pk_mul_f32 v[50:51], v[152:153], v[50:51]
	v_pk_mul_f32 v[52:53], v[154:155], v[52:53]
	v_cvt_pk_bf16_f32 v50, v50, v51
	s_nop 0
	v_cvt_pk_bf16_f32 v51, v52, v53
	global_store_dwordx2 v[70:71], v[50:51], off offset:288
	s_and_saveexec_b64 s[36:37], s[8:9]
	s_cbranch_execz .LBB0_1919
	s_waitcnt lgkmcnt(0)
	v_add_f32_e32 v48, v48, v49
	ds_write_b32 v184, v48 offset:2048
; __device__ __forceinline__ unsigned cvt_pk_bf16(float lo, float hi) { unsigned r; asm volatile("v_cvt_pk_bf16_f32 %0, %1, %2" : "=v"(r) : "v"(lo), "v"(hi)); return r; }
; __device__ __forceinline__ float shx(float v, int o, int lane) { return __int_as_float(__builtin_amdgcn_ds_bpermute((lane ^ o) << 2, __float_as_int(v))); }
;     __device__ __forceinline__ void operator()(const f32x4 (&acc)[2][2][4][2], const Unit& u, int wr, int wc, int fr, int fq) const {
;     ...
;             for (int m = 0; m < 4; ++m) { const int row = row0 + ai * HALF + m * 16; const size_t off = (size_t)row * DM + col0; float ss = 0.f;
; #pragma unroll
;                 for (int bj = 0; bj < 2; ++bj)
; #pragma unroll
;                     for (int n = 0; n < 2; ++n) { const f32x4 x = *(const f32x4*)(src + off + bj * HALF + n * 16) + gv[bj][n] * acc[ai][bj][m][n];
;                         *(f32x4*)(dst + off + bj * HALF + n * 16) = x; ss += (x[0] * x[0] + x[1] * x[1]) + (x[2] * x[2] + x[3] * x[3]);
;                         const f32x4 hh = x * gs[bj][n]; u32x2 w; w.x = cvt_pk_bf16(hh[0], hh[1]); w.y = cvt_pk_bf16(hh[2], hh[3]); *(u32x2*)(Hn + off + bj * HALF + n * 16) = w; }
;                 ss += shx(ss, 16, lane); ss += shx(ss, 32, lane);
;                 if (fq == 0) scr[(ai * HALF + wr * 64 + m * 16 + fr) * 4 + wc] = ss; }
.LBB0_1919:
	s_or_b64 exec, exec, s[36:37]
	s_mov_b64 s[36:37], 0x24000
	v_lshl_add_u64 v[52:53], v[64:65], 0, s[36:37]
	v_lshl_add_u64 v[54:55], v[52:53], 2, s[16:17]
	s_waitcnt lgkmcnt(0)
	v_lshl_add_u64 v[52:53], v[52:53], 1, s[14:15]
	s_waitcnt vmcnt(17)
	v_pk_fma_f32 v[44:45], v[44:45], v[92:93], v[212:213]
	v_pk_fma_f32 v[46:47], v[46:47], v[94:95], v[214:215]
	v_pk_mul_f32 v[50:51], v[166:167], v[44:45]
	global_store_dwordx4 v[54:55], v[44:47], off nt
	v_pk_mul_f32 v[48:49], v[164:165], v[46:47]
	v_cvt_pk_bf16_f32 v50, v50, v51
	s_nop 0
	v_cvt_pk_bf16_f32 v51, v48, v49
	global_store_dwordx2 v[52:53], v[50:51], off
	v_mul_f32_e32 v45, v45, v45
	v_mul_f32_e32 v47, v47, v47
	v_fmac_f32_e32 v45, v44, v44
	v_fmac_f32_e32 v47, v46, v46
	v_add_f32_e32 v44, v45, v47
	s_waitcnt vmcnt(18)
	v_pk_fma_f32 v[40:41], v[40:41], v[88:89], v[216:217]
	v_pk_fma_f32 v[42:43], v[42:43], v[90:91], v[218:219]
	v_pk_mul_f32 v[50:51], v[162:163], v[40:41]
	global_store_dwordx4 v[54:55], v[40:43], off offset:64 nt
	v_pk_mul_f32 v[48:49], v[160:161], v[42:43]
	v_cvt_pk_bf16_f32 v50, v50, v51
	s_nop 0
	v_cvt_pk_bf16_f32 v51, v48, v49
	global_store_dwordx2 v[52:53], v[50:51], off offset:32
	v_mul_f32_e32 v41, v41, v41
	v_mul_f32_e32 v43, v43, v43
	v_fmac_f32_e32 v41, v40, v40
	v_fmac_f32_e32 v43, v42, v42
	v_add_f32_e32 v40, v41, v43
	v_add_f32_e32 v40, v44, v40
	s_waitcnt vmcnt(19)
	v_pk_fma_f32 v[36:37], v[36:37], v[80:81], v[220:221]
	v_pk_fma_f32 v[38:39], v[38:39], v[82:83], v[222:223]
	v_pk_mul_f32 v[50:51], v[158:159], v[36:37]
	global_store_dwordx4 v[54:55], v[36:39], off offset:512 nt
	v_pk_mul_f32 v[48:49], v[156:157], v[38:39]
	v_cvt_pk_bf16_f32 v50, v50, v51
	s_nop 0
	v_cvt_pk_bf16_f32 v51, v48, v49
	global_store_dwordx2 v[52:53], v[50:51], off offset:256
	v_mul_f32_e32 v37, v37, v37
	v_mul_f32_e32 v39, v39, v39
	v_fmac_f32_e32 v37, v36, v36
	v_fmac_f32_e32 v39, v38, v38
	v_add_f32_e32 v36, v37, v39
	v_add_f32_e32 v38, v40, v36
	s_waitcnt vmcnt(20)
	v_pk_fma_f32 v[36:37], v[34:35], v[74:75], v[226:227]
	v_pk_fma_f32 v[34:35], v[32:33], v[72:73], v[224:225]
	v_add_u32_e32 v229, 0xb0000, v228
	global_load_dwordx4 v[212:215], v229, s[16:17] nt
	global_load_dwordx4 v[216:219], v229, s[16:17] offset:64 nt
	global_load_dwordx4 v[220:223], v229, s[16:17] offset:512 nt
	global_load_dwordx4 v[224:227], v229, s[16:17] offset:576 nt
	v_mul_f32_e32 v33, v37, v37
	v_mul_f32_e32 v32, v35, v35
	v_fmac_f32_e32 v32, v34, v34
	v_fmac_f32_e32 v33, v36, v36
	v_add_f32_e32 v32, v32, v33
	v_add_f32_e32 v32, v38, v32
	ds_bpermute_b32 v33, v182, v32
	global_store_dwordx4 v[54:55], v[34:37], off offset:576 nt
	s_waitcnt lgkmcnt(0)
	v_add_f32_e32 v32, v32, v33
	ds_bpermute_b32 v33, v183, v32
	v_pk_mul_f32 v[34:35], v[152:153], v[34:35]
	v_pk_mul_f32 v[36:37], v[154:155], v[36:37]
	v_cvt_pk_bf16_f32 v34, v34, v35
	s_nop 0
	v_cvt_pk_bf16_f32 v35, v36, v37
	global_store_dwordx2 v[52:53], v[34:35], off offset:288
	s_and_saveexec_b64 s[36:37], s[8:9]
	s_cbranch_execz .LBB0_1921
	s_waitcnt lgkmcnt(0)
	v_add_f32_e32 v32, v32, v33
	ds_write_b32 v184, v32 offset:2304
; __device__ __forceinline__ unsigned cvt_pk_bf16(float lo, float hi) { unsigned r; asm volatile("v_cvt_pk_bf16_f32 %0, %1, %2" : "=v"(r) : "v"(lo), "v"(hi)); return r; }
; __device__ __forceinline__ float shx(float v, int o, int lane) { return __int_as_float(__builtin_amdgcn_ds_bpermute((lane ^ o) << 2, __float_as_int(v))); }
; #define PG8_LAS __attribute__((address_space(3)))
;     __device__ __forceinline__ void operator()(const f32x4 (&acc)[2][2][4][2], const Unit& u, int wr, int wc, int fr, int fq) const {
;     ...
;             for (int m = 0; m < 4; ++m) { const int row = row0 + ai * HALF + m * 16; const size_t off = (size_t)row * DM + col0; float ss = 0.f;
; #pragma unroll
;                 for (int bj = 0; bj < 2; ++bj)
; #pragma unroll
;                     for (int n = 0; n < 2; ++n) { const f32x4 x = *(const f32x4*)(src + off + bj * HALF + n * 16) + gv[bj][n] * acc[ai][bj][m][n];
;                         *(f32x4*)(dst + off + bj * HALF + n * 16) = x; ss += (x[0] * x[0] + x[1] * x[1]) + (x[2] * x[2] + x[3] * x[3]);
;                         const f32x4 hh = x * gs[bj][n]; u32x2 w; w.x = cvt_pk_bf16(hh[0], hh[1]); w.y = cvt_pk_bf16(hh[2], hh[3]); *(u32x2*)(Hn + off + bj * HALF + n * 16) = w; }
;                 ss += shx(ss, 16, lane); ss += shx(ss, 32, lane);
;                 if (fq == 0) scr[(ai * HALF + wr * 64 + m * 16 + fr) * 4 + wc] = ss; }
;         asm volatile("s_waitcnt lgkmcnt(0)" ::: "memory"); __builtin_amdgcn_s_barrier(); asm volatile("" ::: "memory");
;         if (lane < 32) { const int rl = 32 * (wr * 4 + wc) + lane; const f32x4 p = *(const PG8_LAS f32x4*)(scr + rl * 4); atomicAdd(ssq + u.pm * BM + rl, (p[0] + p[1]) + (p[2] + p[3])); }
.LBB0_1921:
	s_or_b64 exec, exec, s[36:37]
	s_waitcnt lgkmcnt(0)
	v_lshlrev_b64 v[32:33], 10, v[170:171]
	v_lshl_add_u64 v[32:33], v[32:33], 0, v[168:169]
	s_mov_b64 s[36:37], 0x28000
	v_lshl_add_u64 v[38:39], v[32:33], 0, s[36:37]
	v_lshl_add_u64 v[40:41], v[38:39], 2, s[16:17]
	v_lshl_add_u64 v[38:39], v[38:39], 1, s[14:15]
	s_waitcnt vmcnt(17)
	v_pk_fma_f32 v[28:29], v[28:29], v[92:93], v[196:197]
	v_pk_fma_f32 v[30:31], v[30:31], v[94:95], v[198:199]
	v_pk_mul_f32 v[36:37], v[166:167], v[28:29]
	global_store_dwordx4 v[40:41], v[28:31], off nt
	v_pk_mul_f32 v[34:35], v[164:165], v[30:31]
	v_cvt_pk_bf16_f32 v36, v36, v37
	s_nop 0
	v_cvt_pk_bf16_f32 v37, v34, v35
	global_store_dwordx2 v[38:39], v[36:37], off
	v_mul_f32_e32 v29, v29, v29
	v_mul_f32_e32 v31, v31, v31
	v_fmac_f32_e32 v29, v28, v28
	v_fmac_f32_e32 v31, v30, v30
	v_add_f32_e32 v28, v29, v31
	s_waitcnt vmcnt(18)
	v_pk_fma_f32 v[24:25], v[24:25], v[88:89], v[200:201]
	v_pk_fma_f32 v[26:27], v[26:27], v[90:91], v[202:203]
	v_pk_mul_f32 v[36:37], v[162:163], v[24:25]
	global_store_dwordx4 v[40:41], v[24:27], off offset:64 nt
	v_pk_mul_f32 v[34:35], v[160:161], v[26:27]
	v_cvt_pk_bf16_f32 v36, v36, v37
	s_nop 0
	v_cvt_pk_bf16_f32 v37, v34, v35
	global_store_dwordx2 v[38:39], v[36:37], off offset:32
	v_mul_f32_e32 v25, v25, v25
	v_mul_f32_e32 v27, v27, v27
	v_fmac_f32_e32 v25, v24, v24
	v_fmac_f32_e32 v27, v26, v26
	v_add_f32_e32 v24, v25, v27
	v_add_f32_e32 v24, v28, v24
	s_waitcnt vmcnt(19)
	v_pk_fma_f32 v[20:21], v[20:21], v[80:81], v[204:205]
	v_pk_fma_f32 v[22:23], v[22:23], v[82:83], v[206:207]
	v_pk_mul_f32 v[36:37], v[158:159], v[20:21]
	global_store_dwordx4 v[40:41], v[20:23], off offset:512 nt
	v_pk_mul_f32 v[34:35], v[156:157], v[22:23]
	v_cvt_pk_bf16_f32 v36, v36, v37
	s_nop 0
	v_cvt_pk_bf16_f32 v37, v34, v35
	global_store_dwordx2 v[38:39], v[36:37], off offset:256
	v_mul_f32_e32 v21, v21, v21
	v_mul_f32_e32 v23, v23, v23
	v_fmac_f32_e32 v21, v20, v20
	v_fmac_f32_e32 v23, v22, v22
	v_add_f32_e32 v20, v21, v23
	v_add_f32_e32 v22, v24, v20
	s_waitcnt vmcnt(20)
	v_pk_fma_f32 v[20:21], v[18:19], v[74:75], v[210:211]
	v_pk_fma_f32 v[18:19], v[16:17], v[72:73], v[208:209]
	v_mul_f32_e32 v17, v21, v21
	v_mul_f32_e32 v16, v19, v19
	v_fmac_f32_e32 v16, v18, v18
	v_fmac_f32_e32 v17, v20, v20
	v_add_f32_e32 v16, v16, v17
	v_add_f32_e32 v16, v22, v16
	ds_bpermute_b32 v17, v182, v16
	global_store_dwordx4 v[40:41], v[18:21], off offset:576 nt
	s_waitcnt lgkmcnt(0)
	v_add_f32_e32 v16, v16, v17
	ds_bpermute_b32 v17, v183, v16
	v_pk_mul_f32 v[18:19], v[152:153], v[18:19]
	v_pk_mul_f32 v[20:21], v[154:155], v[20:21]
	v_cvt_pk_bf16_f32 v18, v18, v19
	s_nop 0
	v_cvt_pk_bf16_f32 v19, v20, v21
	global_store_dwordx2 v[38:39], v[18:19], off offset:288
	s_and_saveexec_b64 s[36:37], s[8:9]
	s_cbranch_execz .LBB0_1923
	s_waitcnt lgkmcnt(0)
	v_add_f32_e32 v16, v16, v17
	ds_write_b32 v184, v16 offset:2560
.LBB0_1923:
	s_or_b64 exec, exec, s[36:37]
	s_mov_b64 s[36:37], 0x2c000
	v_lshl_add_u64 v[20:21], v[32:33], 0, s[36:37]
	v_lshl_add_u64 v[22:23], v[20:21], 2, s[16:17]
	s_waitcnt lgkmcnt(0)
	v_lshl_add_u64 v[20:21], v[20:21], 1, s[14:15]
	s_waitcnt vmcnt(13)
	v_pk_fma_f32 v[12:13], v[12:13], v[92:93], v[212:213]
	v_pk_fma_f32 v[14:15], v[14:15], v[94:95], v[214:215]
	v_pk_mul_f32 v[18:19], v[166:167], v[12:13]
	global_store_dwordx4 v[22:23], v[12:15], off nt
	v_pk_mul_f32 v[16:17], v[164:165], v[14:15]
	v_cvt_pk_bf16_f32 v18, v18, v19
	s_nop 0
	v_cvt_pk_bf16_f32 v19, v16, v17
	global_store_dwordx2 v[20:21], v[18:19], off
	v_mul_f32_e32 v13, v13, v13
	v_mul_f32_e32 v15, v15, v15
	v_fmac_f32_e32 v13, v12, v12
	v_fmac_f32_e32 v15, v14, v14
	v_add_f32_e32 v12, v13, v15
	s_waitcnt vmcnt(14)
	v_pk_fma_f32 v[8:9], v[8:9], v[88:89], v[216:217]
	v_pk_fma_f32 v[10:11], v[10:11], v[90:91], v[218:219]
	v_pk_mul_f32 v[18:19], v[162:163], v[8:9]
	global_store_dwordx4 v[22:23], v[8:11], off offset:64 nt
	v_pk_mul_f32 v[16:17], v[160:161], v[10:11]
	v_cvt_pk_bf16_f32 v18, v18, v19
	s_nop 0
	v_cvt_pk_bf16_f32 v19, v16, v17
	global_store_dwordx2 v[20:21], v[18:19], off offset:32
	v_mul_f32_e32 v9, v9, v9
	v_mul_f32_e32 v11, v11, v11
	v_fmac_f32_e32 v9, v8, v8
	v_fmac_f32_e32 v11, v10, v10
	v_add_f32_e32 v8, v9, v11
	v_add_f32_e32 v8, v12, v8
	s_waitcnt vmcnt(15)
	v_pk_fma_f32 v[4:5], v[4:5], v[80:81], v[220:221]
	v_pk_fma_f32 v[6:7], v[6:7], v[82:83], v[222:223]
	v_pk_mul_f32 v[18:19], v[158:159], v[4:5]
	global_store_dwordx4 v[22:23], v[4:7], off offset:512 nt
	v_pk_mul_f32 v[16:17], v[156:157], v[6:7]
	v_cvt_pk_bf16_f32 v18, v18, v19
	s_nop 0
	v_cvt_pk_bf16_f32 v19, v16, v17
	global_store_dwordx2 v[20:21], v[18:19], off offset:256
	v_mul_f32_e32 v5, v5, v5
	v_mul_f32_e32 v7, v7, v7
	v_fmac_f32_e32 v5, v4, v4
	v_fmac_f32_e32 v7, v6, v6
	v_add_f32_e32 v4, v5, v7
	v_add_f32_e32 v6, v8, v4
	s_waitcnt vmcnt(16)
	v_pk_fma_f32 v[4:5], v[2:3], v[74:75], v[226:227]
	v_pk_fma_f32 v[2:3], v[0:1], v[72:73], v[224:225]
	v_mul_f32_e32 v1, v5, v5
	v_mul_f32_e32 v0, v3, v3
	v_fmac_f32_e32 v0, v2, v2
	v_fmac_f32_e32 v1, v4, v4
	v_add_f32_e32 v0, v0, v1
	v_add_f32_e32 v0, v6, v0
	ds_bpermute_b32 v1, v182, v0
	global_store_dwordx4 v[22:23], v[2:5], off offset:576 nt
	s_waitcnt lgkmcnt(0)
	v_add_f32_e32 v0, v0, v1
	ds_bpermute_b32 v1, v183, v0
	v_pk_mul_f32 v[2:3], v[152:153], v[2:3]
	v_pk_mul_f32 v[4:5], v[154:155], v[4:5]
	v_cvt_pk_bf16_f32 v2, v2, v3
	s_nop 0
	v_cvt_pk_bf16_f32 v3, v4, v5
	global_store_dwordx2 v[20:21], v[2:3], off offset:288
	s_and_saveexec_b64 s[36:37], s[8:9]
	s_cbranch_execz .LBB0_1925
	s_waitcnt lgkmcnt(0)
	v_add_f32_e32 v0, v0, v1
	ds_write_b32 v184, v0 offset:2816
